# GEMM tile loops (A, D, E, F): the 8 LDS-DMA loads of a k-tile issued back to back with 32-bit lane offsets from the workspace base and scalar M0 updates
# baseline (speedup 1.0000x reference)
; __device__ __forceinline__ int opaque_tid() { int t = threadIdx.x; asm volatile("" : "+v"(t)); return t; }
; __device__ __forceinline__ void gemm_mainloop_d(const bf16_t* __restrict__ Ap, int lda, const bf16_t* __restrict__ Bt, int K,
;                                                 int m0, int n0, f32x4 (&acc)[4][4], char* lds) {
;   const int tid = opaque_tid(), lane = tid & 63, wid = tid >> 6, wr = wid >> 1, wc = wid & 1, fr = lane & 15, fq = lane >> 4;
; #pragma unroll
;   for (int m = 0; m < 4; m++)
; #pragma unroll
;     for (int n = 0; n < 4; n++) acc[m][n] = (f32x4){0.f, 0.f, 0.f, 0.f};
;   const int nk = K >> 6;
;   const int lrow = tid >> 3, cph = tid & 7;
;   auto dma = [&](int kt, int st) {
;     char* la = lds + st * 32768; char* lb = la + 16384;
; #pragma unroll
;     for (int i = 0; i < 4; i++) {
;       const int row = i * 32 + lrow; const int c = cph ^ ((row >> 1) & 7);
;       __builtin_amdgcn_global_load_lds((const unsigned*)(Ap + (size_t)(m0 + row) * lda + kt * 64 + c * 8), (__attribute__((address_space(3))) unsigned*)(la + i * 4096 + tid * 16), 16, 0, 0);
;       __builtin_amdgcn_global_load_lds((const unsigned*)(Bt + (size_t)(n0 + row) * K + kt * 64 + c * 8), (__attribute__((address_space(3))) unsigned*)(lb + i * 4096 + tid * 16), 16, 0, 0);
;     }
;   };
;   dma(0, 0);
;   asm volatile("s_waitcnt vmcnt(0)" ::: "memory"); __builtin_amdgcn_s_barrier(); asm volatile("" ::: "memory");
.LBB0_94:
	s_and_b32 s29, s35, 0xffffff80
	s_and_b32 s37, s34, 0x380
	s_mov_b32 s40, 0
	s_add_u32 s2, s46, s40
	s_addc_u32 s3, s47, 0
	s_add_u32 s24, s2, 0x768000
	s_addc_u32 s25, s3, 0
	s_mov_b32 s41, 0
	s_add_u32 s2, s46, s41
	s_addc_u32 s3, s47, 0
	s_add_u32 s38, s2, 0xf3cc000
	s_mov_b32 s27, 0
	s_mov_b32 s28, 0
	v_mov_b32_e32 v8, v198
	s_addc_u32 s39, s3, 0
	s_lshl_b32 s2, s36, 4
	s_and_b32 s3, s2, 0xffffff80
	v_ashrrev_i32_e32 v11, 3, v8
	v_lshrrev_b32_e32 v12, 1, v11
	v_xor_b32_e32 v2, v12, v8
	s_waitcnt vmcnt(5)
	v_add_u32_e32 v4, s3, v11
	s_waitcnt vmcnt(4)
	v_mov_b64_e32 v[0:1], s[24:25]
	v_mad_i64_i32 v[4:5], s[24:25], v4, s33, v[0:1]
	v_lshlrev_b32_e32 v2, 4, v2
	v_lshl_add_u32 v82, v8, 4, 0
	s_lshl_b32 s2, s36, 7
	v_and_b32_e32 v2, 0x70, v2
	v_readfirstlane_b32 s24, v82
	s_and_b32 s2, s2, 0x380
	v_lshl_add_u64 v[4:5], v[4:5], 0, v[2:3]
	s_mov_b32 m0, s24
	v_add_u32_e32 v6, s2, v11
	global_load_lds_dwordx4 v[4:5], off
	v_mov_b64_e32 v[4:5], s[38:39]
	v_mad_i64_i32 v[6:7], s[24:25], v6, s33, v[4:5]
	v_add_u32_e32 v13, 0x4000, v82
	v_lshl_add_u64 v[6:7], v[6:7], 0, v[2:3]
	v_readfirstlane_b32 s24, v13
	s_mov_b32 m0, s24
	v_add_u32_e32 v13, 32, v11
	global_load_lds_dwordx4 v[6:7], off
	v_add_u32_e32 v6, s3, v13
	v_mad_i64_i32 v[6:7], s[24:25], v6, s33, v[0:1]
	v_add_u32_e32 v14, 0x1000, v82
	v_lshl_add_u64 v[6:7], v[6:7], 0, v[2:3]
	v_readfirstlane_b32 s24, v14
	s_mov_b32 m0, s24
	v_add_u32_e32 v14, 0x5000, v82
	global_load_lds_dwordx4 v[6:7], off
	v_add_u32_e32 v6, s2, v13
	v_mad_i64_i32 v[6:7], s[24:25], v6, s33, v[4:5]
	v_readfirstlane_b32 s24, v14
	v_lshl_add_u64 v[6:7], v[6:7], 0, v[2:3]
	s_mov_b32 m0, s24
	v_add_u32_e32 v14, 64, v11
	global_load_lds_dwordx4 v[6:7], off
	v_add_u32_e32 v6, s3, v14
	v_mad_i64_i32 v[6:7], s[24:25], v6, s33, v[0:1]
	v_add_u32_e32 v15, 0x2000, v82
	v_lshl_add_u64 v[6:7], v[6:7], 0, v[2:3]
	v_readfirstlane_b32 s24, v15
	s_mov_b32 m0, s24
	v_add_u32_e32 v15, 0x6000, v82
	global_load_lds_dwordx4 v[6:7], off
	v_add_u32_e32 v6, s2, v14
	v_mad_i64_i32 v[6:7], s[24:25], v6, s33, v[4:5]
	v_readfirstlane_b32 s24, v15
	v_lshl_add_u64 v[6:7], v[6:7], 0, v[2:3]
	s_mov_b32 m0, s24
	s_mov_b32 s4, 0x1ffffc0
	global_load_lds_dwordx4 v[6:7], off
	v_add_u32_e32 v6, 0x60, v11
	v_add_u32_e32 v7, s3, v6
	v_mad_i64_i32 v[0:1], s[24:25], v7, s33, v[0:1]
	v_add_u32_e32 v7, 0x3000, v82
	v_lshl_add_u64 v[0:1], v[0:1], 0, v[2:3]
	v_readfirstlane_b32 s24, v7
	s_mov_b32 m0, s24
	v_lshrrev_b32_e32 v9, 4, v8
	global_load_lds_dwordx4 v[0:1], off
	v_add_u32_e32 v0, s2, v6
	v_mad_i64_i32 v[0:1], s[24:25], v0, s33, v[4:5]
	v_lshl_add_u64 v[0:1], v[0:1], 0, v[2:3]
	v_add_u32_e32 v2, 0x7000, v82
	v_bfe_u32 v10, v8, 4, 2
	v_readfirstlane_b32 s24, v2
	s_mov_b32 m0, s24
	v_lshlrev_b32_e32 v2, 7, v8
	global_load_lds_dwordx4 v[0:1], off
	v_and_b32_e32 v0, 15, v8
	v_lshrrev_b32_e32 v1, 1, v8
	v_and_or_b32 v0, v1, s4, v0
	v_bfe_u32 v1, v8, 1, 3
	v_bitop3_b32 v4, v9, v1, 3 bitop3:0x6c
	v_bitop3_b32 v1, v10, v1, 4 bitop3:0x36
	v_lshlrev_b32_e32 v4, 4, v4
	v_lshlrev_b32_e32 v0, 7, v0
	v_lshlrev_b32_e32 v1, 4, v1
	v_and_b32_e32 v2, 0x2780, v2
	v_or_b32_e32 v85, v0, v4
	v_or_b32_e32 v83, v1, v0
	v_add_u32_e32 v0, s29, v11
	v_or_b32_e32 v84, v4, v2
	v_or_b32_e32 v2, v1, v2
	v_mad_i64_i32 v[0:1], s[24:25], v0, s33, 0
	v_bitop3_b32 v4, v12, 7, v8 bitop3:0x48
	v_readlane_b32 s4, v254, 39
	v_lshlrev_b32_e32 v7, 4, v4
	s_add_u32 s24, s4, s40
	v_readlane_b32 s4, v254, 40
	v_add_u32_e32 v4, s37, v11
	s_addc_u32 s25, s4, 0
	v_mad_i64_i32 v[4:5], s[38:39], v4, s33, 0
	v_readlane_b32 s4, v254, 41
	s_add_u32 s38, s4, s41
	v_readlane_b32 s4, v254, 42
	v_or_b32_e32 v4, v4, v7
	s_addc_u32 s39, s4, 0
	s_waitcnt vmcnt(0)
	v_lshl_add_u64 v[68:69], s[38:39], 0, v[4:5]
	v_add_u32_e32 v4, s29, v13
	v_mad_i64_i32 v[4:5], s[40:41], v4, s33, 0
	v_or_b32_e32 v4, v4, v7
	v_lshl_add_u64 v[70:71], s[24:25], 0, v[4:5]
	v_add_u32_e32 v4, s37, v13
	v_mad_i64_i32 v[4:5], s[40:41], v4, s33, 0
	v_or_b32_e32 v4, v4, v7
	v_lshl_add_u64 v[72:73], s[38:39], 0, v[4:5]
	v_add_u32_e32 v4, s29, v14
	v_mad_i64_i32 v[4:5], s[40:41], v4, s33, 0
	v_or_b32_e32 v4, v4, v7
	v_lshl_add_u64 v[74:75], s[24:25], 0, v[4:5]
	v_add_u32_e32 v4, s37, v14
	v_mad_i64_i32 v[4:5], s[40:41], v4, s33, 0
	v_or_b32_e32 v4, v4, v7
	v_lshl_add_u64 v[76:77], s[38:39], 0, v[4:5]
	v_add_u32_e32 v4, s29, v6
	v_mad_i64_i32 v[4:5], s[40:41], v4, s33, 0
	v_or_b32_e32 v4, v4, v7
	v_or_b32_e32 v0, v0, v7
	v_lshl_add_u64 v[78:79], s[24:25], 0, v[4:5]
	v_add_u32_e32 v4, s37, v6
	v_lshl_add_u64 v[0:1], s[24:25], 0, v[0:1]
	v_mad_i64_i32 v[4:5], s[24:25], v4, s33, 0
	s_waitcnt vmcnt(0)
	s_barrier
	v_or_b32_e32 v4, v4, v7
	v_lshl_add_u64 v[80:81], s[38:39], 0, v[4:5]
	v_mov_b32_e32 v4, 0
	s_mov_b32 s26, 0
	s_mov_b64 s[24:25], 0
	v_mov_b32_e32 v5, v4
	v_mov_b32_e32 v6, v4
	v_mov_b32_e32 v7, v4
	v_mov_b32_e32 v8, v4
	v_mov_b32_e32 v9, v4
	v_mov_b32_e32 v10, v4
	v_mov_b32_e32 v11, v4
	v_mov_b32_e32 v12, v4
	v_mov_b32_e32 v13, v4
	v_mov_b32_e32 v14, v4
	v_mov_b32_e32 v15, v4
	v_mov_b32_e32 v16, v4
	v_mov_b32_e32 v17, v4
	v_mov_b32_e32 v18, v4
	v_mov_b32_e32 v19, v4
	v_mov_b32_e32 v20, v4
	v_mov_b32_e32 v21, v4
	v_mov_b32_e32 v22, v4
	v_mov_b32_e32 v23, v4
	v_mov_b32_e32 v24, v4
	v_mov_b32_e32 v25, v4
	v_mov_b32_e32 v26, v4
	v_mov_b32_e32 v27, v4
	v_mov_b32_e32 v28, v4
	v_mov_b32_e32 v29, v4
	v_mov_b32_e32 v30, v4
	v_mov_b32_e32 v31, v4
	v_mov_b32_e32 v32, v4
	v_mov_b32_e32 v33, v4
	v_mov_b32_e32 v34, v4
	v_mov_b32_e32 v35, v4
	v_mov_b32_e32 v36, v4
	v_mov_b32_e32 v37, v4
	v_mov_b32_e32 v38, v4
	v_mov_b32_e32 v39, v4
	v_mov_b32_e32 v40, v4
	v_mov_b32_e32 v41, v4
	v_mov_b32_e32 v42, v4
	v_mov_b32_e32 v43, v4
	v_mov_b32_e32 v44, v4
	v_mov_b32_e32 v45, v4
	v_mov_b32_e32 v46, v4
	v_mov_b32_e32 v47, v4
	v_mov_b32_e32 v48, v4
	v_mov_b32_e32 v49, v4
	v_mov_b32_e32 v50, v4
	v_mov_b32_e32 v51, v4
	v_mov_b32_e32 v52, v4
	v_mov_b32_e32 v53, v4
	v_mov_b32_e32 v54, v4
	v_mov_b32_e32 v55, v4
	v_mov_b32_e32 v56, v4
	v_mov_b32_e32 v57, v4
	v_mov_b32_e32 v58, v4
	v_mov_b32_e32 v59, v4
	v_mov_b32_e32 v60, v4
	v_mov_b32_e32 v61, v4
	v_mov_b32_e32 v62, v4
	v_mov_b32_e32 v63, v4
	v_mov_b32_e32 v64, v4
	v_mov_b32_e32 v65, v4
	v_mov_b32_e32 v66, v4
	v_mov_b32_e32 v67, v4
	v_subrev_u32_e32 v150, s46, v0
	v_subrev_u32_e32 v151, s46, v68
	v_subrev_u32_e32 v152, s46, v70
	v_subrev_u32_e32 v153, s46, v72
	v_subrev_u32_e32 v154, s46, v74
	v_subrev_u32_e32 v155, s46, v76
	v_subrev_u32_e32 v156, s46, v78
	v_subrev_u32_e32 v157, s46, v80
	v_readfirstlane_b32 vcc_hi, v82
; __device__ __forceinline__ void gemm_mainloop_d(const bf16_t* __restrict__ Ap, int lda, const bf16_t* __restrict__ Bt, int K,
;                                                 int m0, int n0, f32x4 (&acc)[4][4], char* lds) {
;     ...
;   auto dma = [&](int kt, int st) {
;     char* la = lds + st * 32768; char* lb = la + 16384;
; #pragma unroll
;     for (int i = 0; i < 4; i++) {
;       const int row = i * 32 + lrow; const int c = cph ^ ((row >> 1) & 7);
;       __builtin_amdgcn_global_load_lds((const unsigned*)(Ap + (size_t)(m0 + row) * lda + kt * 64 + c * 8), (__attribute__((address_space(3))) unsigned*)(la + i * 4096 + tid * 16), 16, 0, 0);
;       __builtin_amdgcn_global_load_lds((const unsigned*)(Bt + (size_t)(n0 + row) * K + kt * 64 + c * 8), (__attribute__((address_space(3))) unsigned*)(lb + i * 4096 + tid * 16), 16, 0, 0);
;     }
;   };
;   dma(0, 0);
;   asm volatile("s_waitcnt vmcnt(0)" ::: "memory"); __builtin_amdgcn_s_barrier(); asm volatile("" ::: "memory");
;   for (int kt = 0; kt < nk; kt++) {
;     const int st = kt & 1;
;     if (kt + 1 < nk) dma(kt + 1, st ^ 1);
;     const char* la = lds + st * 32768; const char* lb = la + 16384;
;     bf16x8 af[2][4], bfv[2][4];
; #pragma unroll
;     for (int kc = 0; kc < 2; kc++) {
; #pragma unroll
;       for (int m = 0; m < 4; m++) { const int row = wr * 64 + m * 16 + fr; af[kc][m] = *(const bf16x8*)(la + (row * 8 + ((kc * 4 + fq) ^ ((row >> 1) & 7))) * 16); }
; #pragma unroll
;       for (int n = 0; n < 4; n++) { const int row = wc * 64 + n * 16 + fr; bfv[kc][n] = *(const bf16x8*)(lb + (row * 8 + ((kc * 4 + fq) ^ ((row >> 1) & 7))) * 16); }
;     }
;     __builtin_amdgcn_s_setprio(1);
; #pragma unroll
;     for (int kc = 0; kc < 2; kc++)
; #pragma unroll
;       for (int m = 0; m < 4; m++)
; #pragma unroll
;         for (int n = 0; n < 4; n++) acc[m][n] = __builtin_amdgcn_mfma_f32_16x16x32_bf16(bfv[kc][n], af[kc][m], acc[m][n], 0, 0, 0);
;     __builtin_amdgcn_s_setprio(0);
;     asm volatile("s_waitcnt vmcnt(0) lgkmcnt(0)" ::: "memory"); __builtin_amdgcn_s_barrier(); asm volatile("" ::: "memory");
;   }
.LBB0_95:
	s_and_b32 s29, s26, 0x8000
	s_xor_b32 s37, s29, 0x8000
	s_add_i32 s37, s37, vcc_hi
	s_mov_b32 m0, s37
	s_add_i32 vcc_lo, s37, 0x4000
	global_load_lds_dwordx4 v150, s[46:47]
	s_mov_b32 m0, vcc_lo
	s_add_i32 vcc_lo, s37, 0x1000
	global_load_lds_dwordx4 v151, s[46:47]
	s_mov_b32 m0, vcc_lo
	s_add_i32 vcc_lo, s37, 0x5000
	global_load_lds_dwordx4 v152, s[46:47]
	s_mov_b32 m0, vcc_lo
	s_add_i32 vcc_lo, s37, 0x2000
	global_load_lds_dwordx4 v153, s[46:47]
	s_mov_b32 m0, vcc_lo
	s_add_i32 vcc_lo, s37, 0x6000
	global_load_lds_dwordx4 v154, s[46:47]
	s_mov_b32 m0, vcc_lo
	s_add_i32 vcc_lo, s37, 0x3000
	global_load_lds_dwordx4 v155, s[46:47]
	s_mov_b32 m0, vcc_lo
	s_add_i32 vcc_lo, s37, 0x7000
	global_load_lds_dwordx4 v156, s[46:47]
	s_mov_b32 m0, vcc_lo
	s_nop 0
	global_load_lds_dwordx4 v157, s[46:47]
	v_add_u32_e32 v150, 0x80, v150
	v_add_u32_e32 v151, 0x80, v151
	v_add_u32_e32 v152, 0x80, v152
	v_add_u32_e32 v153, 0x80, v153
	v_add_u32_e32 v154, 0x80, v154
	v_add_u32_e32 v155, 0x80, v155
	v_add_u32_e32 v156, 0x80, v156
	v_add_u32_e32 v157, 0x80, v157
	v_add_u32_e32 v98, s29, v85
	v_add_u32_e32 v114, s29, v84
	v_add_u32_e32 v130, s29, v83
	v_add_u32_e32 v146, s29, v2
	ds_read_b128 v[86:89], v98
	ds_read_b128 v[90:93], v98 offset:2048
	ds_read_b128 v[94:97], v98 offset:4096
	ds_read_b128 v[98:101], v98 offset:6144
	ds_read_b128 v[102:105], v114 offset:16384
	ds_read_b128 v[106:109], v114 offset:18432
	ds_read_b128 v[110:113], v114 offset:20480
	ds_read_b128 v[114:117], v114 offset:22528
	ds_read_b128 v[118:121], v130
	ds_read_b128 v[122:125], v130 offset:2048
	ds_read_b128 v[126:129], v130 offset:4096
	ds_read_b128 v[130:133], v130 offset:6144
	ds_read_b128 v[134:137], v146 offset:16384
	ds_read_b128 v[138:141], v146 offset:18432
	ds_read_b128 v[142:145], v146 offset:20480
	ds_read_b128 v[146:149], v146 offset:22528
	s_setprio 1
	s_waitcnt lgkmcnt(0)
	v_mfma_f32_16x16x32_bf16 v[64:67], v[102:105], v[86:89], v[64:67]
	v_mfma_f32_16x16x32_bf16 v[60:63], v[106:109], v[86:89], v[60:63]
	v_mfma_f32_16x16x32_bf16 v[56:59], v[110:113], v[86:89], v[56:59]
	v_mfma_f32_16x16x32_bf16 v[52:55], v[114:117], v[86:89], v[52:55]
	v_mfma_f32_16x16x32_bf16 v[48:51], v[102:105], v[90:93], v[48:51]
	v_mfma_f32_16x16x32_bf16 v[44:47], v[106:109], v[90:93], v[44:47]
	v_mfma_f32_16x16x32_bf16 v[40:43], v[110:113], v[90:93], v[40:43]
	v_mfma_f32_16x16x32_bf16 v[36:39], v[114:117], v[90:93], v[36:39]
	v_mfma_f32_16x16x32_bf16 v[32:35], v[102:105], v[94:97], v[32:35]
	v_mfma_f32_16x16x32_bf16 v[28:31], v[106:109], v[94:97], v[28:31]
	v_mfma_f32_16x16x32_bf16 v[24:27], v[110:113], v[94:97], v[24:27]
	v_mfma_f32_16x16x32_bf16 v[20:23], v[114:117], v[94:97], v[20:23]
	v_mfma_f32_16x16x32_bf16 v[16:19], v[102:105], v[98:101], v[16:19]
	v_mfma_f32_16x16x32_bf16 v[12:15], v[106:109], v[98:101], v[12:15]
	v_mfma_f32_16x16x32_bf16 v[8:11], v[110:113], v[98:101], v[8:11]
	v_mfma_f32_16x16x32_bf16 v[4:7], v[114:117], v[98:101], v[4:7]
	v_mfma_f32_16x16x32_bf16 v[64:67], v[134:137], v[118:121], v[64:67]
	v_mfma_f32_16x16x32_bf16 v[60:63], v[138:141], v[118:121], v[60:63]
	v_mfma_f32_16x16x32_bf16 v[56:59], v[142:145], v[118:121], v[56:59]
	v_mfma_f32_16x16x32_bf16 v[52:55], v[146:149], v[118:121], v[52:55]
	v_mfma_f32_16x16x32_bf16 v[48:51], v[134:137], v[122:125], v[48:51]
	v_mfma_f32_16x16x32_bf16 v[44:47], v[138:141], v[122:125], v[44:47]
	v_mfma_f32_16x16x32_bf16 v[40:43], v[142:145], v[122:125], v[40:43]
	v_mfma_f32_16x16x32_bf16 v[36:39], v[146:149], v[122:125], v[36:39]
	v_mfma_f32_16x16x32_bf16 v[32:35], v[134:137], v[126:129], v[32:35]
	v_mfma_f32_16x16x32_bf16 v[28:31], v[138:141], v[126:129], v[28:31]
	v_mfma_f32_16x16x32_bf16 v[24:27], v[142:145], v[126:129], v[24:27]
	v_mfma_f32_16x16x32_bf16 v[20:23], v[146:149], v[126:129], v[20:23]
	v_mfma_f32_16x16x32_bf16 v[16:19], v[134:137], v[130:133], v[16:19]
	v_mfma_f32_16x16x32_bf16 v[12:15], v[138:141], v[130:133], v[12:15]
	v_mfma_f32_16x16x32_bf16 v[8:11], v[142:145], v[130:133], v[8:11]
	v_mfma_f32_16x16x32_bf16 v[4:7], v[146:149], v[130:133], v[4:7]
	s_setprio 0
	s_waitcnt vmcnt(0) lgkmcnt(0)
	s_barrier
	s_add_u32 s24, s24, 0x80
	s_addc_u32 s25, s25, 0
	s_add_i32 s26, s26, 0x8000
	s_cmpk_eq_i32 s24, 0x1580
	s_cbranch_scc0 .LBB0_95
; __device__ __forceinline__ void gemm_mainloop_d(const bf16_t* __restrict__ Ap, int lda, const bf16_t* __restrict__ Bt, int K,
;                                                 int m0, int n0, f32x4 (&acc)[4][4], char* lds) {
;     ...
;     const char* la = lds + st * 32768; const char* lb = la + 16384;
;     bf16x8 af[2][4], bfv[2][4];
; #pragma unroll
;     for (int kc = 0; kc < 2; kc++) {
; #pragma unroll
;       for (int m = 0; m < 4; m++) { const int row = wr * 64 + m * 16 + fr; af[kc][m] = *(const bf16x8*)(la + (row * 8 + ((kc * 4 + fq) ^ ((row >> 1) & 7))) * 16); }
; #pragma unroll
;       for (int n = 0; n < 4; n++) { const int row = wc * 64 + n * 16 + fr; bfv[kc][n] = *(const bf16x8*)(lb + (row * 8 + ((kc * 4 + fq) ^ ((row >> 1) & 7))) * 16); }
;     }
;     __builtin_amdgcn_s_setprio(1);
; #pragma unroll
;     for (int kc = 0; kc < 2; kc++)
; #pragma unroll
;       for (int m = 0; m < 4; m++)
; #pragma unroll
;         for (int n = 0; n < 4; n++) acc[m][n] = __builtin_amdgcn_mfma_f32_16x16x32_bf16(bfv[kc][n], af[kc][m], acc[m][n], 0, 0, 0);
;     __builtin_amdgcn_s_setprio(0);
;     asm volatile("s_waitcnt vmcnt(0) lgkmcnt(0)" ::: "memory"); __builtin_amdgcn_s_barrier(); asm volatile("" ::: "memory");
;   }
	v_add_u32_e32 v0, 0, v85
	ds_read_b128 v[68:71], v0 offset:32768
	ds_read_b128 v[72:75], v0 offset:34816
	ds_read_b128 v[76:79], v0 offset:36864
	ds_read_b128 v[86:89], v0 offset:38912
	v_add_u32_e32 v0, 0, v84
	ds_read_b128 v[90:93], v0 offset:49152
	ds_read_b128 v[94:97], v0 offset:51200
	ds_read_b128 v[98:101], v0 offset:53248
	ds_read_b128 v[102:105], v0 offset:55296
	v_add_u32_e32 v0, 0, v83
	s_add_u32 s24, s46, s27
	ds_read_b128 v[80:83], v0 offset:32768
	ds_read_b128 v[106:109], v0 offset:34816
	ds_read_b128 v[110:113], v0 offset:36864
	ds_read_b128 v[114:117], v0 offset:38912
	v_add_u32_e32 v0, 0, v2
	s_addc_u32 s25, s47, 0
	ds_read_b128 v[118:121], v0 offset:49152
	ds_read_b128 v[122:125], v0 offset:51200
	ds_read_b128 v[126:129], v0 offset:53248
	ds_read_b128 v[130:133], v0 offset:55296
	s_add_u32 s28, s46, s28
	s_addc_u32 s29, s47, 0
	s_add_u32 s26, s24, 0x65a8000
	s_addc_u32 s27, s25, 0
	s_add_u32 s24, s28, 0xff8c000
	s_addc_u32 s25, s29, 0
	s_setprio 1
	s_waitcnt lgkmcnt(0)
	v_mfma_f32_16x16x32_bf16 v[56:59], v[98:101], v[68:71], v[56:59]
	v_mfma_f32_16x16x32_bf16 v[48:51], v[90:93], v[72:75], v[48:51]
	v_mfma_f32_16x16x32_bf16 v[44:47], v[94:97], v[72:75], v[44:47]
	v_mfma_f32_16x16x32_bf16 v[40:43], v[98:101], v[72:75], v[40:43]
	v_mfma_f32_16x16x32_bf16 v[36:39], v[102:105], v[72:75], v[36:39]
	v_mfma_f32_16x16x32_bf16 v[32:35], v[90:93], v[76:79], v[32:35]
	v_mfma_f32_16x16x32_bf16 v[28:31], v[94:97], v[76:79], v[28:31]
	v_mfma_f32_16x16x32_bf16 v[24:27], v[98:101], v[76:79], v[24:27]
	v_mfma_f32_16x16x32_bf16 v[20:23], v[102:105], v[76:79], v[20:23]
	v_mfma_f32_16x16x32_bf16 v[16:19], v[90:93], v[86:89], v[16:19]
	v_mfma_f32_16x16x32_bf16 v[12:15], v[94:97], v[86:89], v[12:15]
	v_mfma_f32_16x16x32_bf16 v[8:11], v[98:101], v[86:89], v[8:11]
	v_mfma_f32_16x16x32_bf16 v[4:7], v[102:105], v[86:89], v[4:7]
	v_mfma_f32_16x16x32_bf16 v[64:67], v[90:93], v[68:71], v[64:67]
	v_mfma_f32_16x16x32_bf16 v[60:63], v[94:97], v[68:71], v[60:63]
	v_mfma_f32_16x16x32_bf16 v[52:55], v[102:105], v[68:71], v[52:55]
	v_mfma_f32_16x16x32_bf16 v[56:59], v[126:129], v[80:83], v[56:59]
	v_mfma_f32_16x16x32_bf16 v[48:51], v[118:121], v[106:109], v[48:51]
	v_mfma_f32_16x16x32_bf16 v[44:47], v[122:125], v[106:109], v[44:47]
	v_mfma_f32_16x16x32_bf16 v[40:43], v[126:129], v[106:109], v[40:43]
	v_mfma_f32_16x16x32_bf16 v[36:39], v[130:133], v[106:109], v[36:39]
	v_mfma_f32_16x16x32_bf16 v[32:35], v[118:121], v[110:113], v[32:35]
	v_mfma_f32_16x16x32_bf16 v[28:31], v[122:125], v[110:113], v[28:31]
	v_mfma_f32_16x16x32_bf16 v[24:27], v[126:129], v[110:113], v[24:27]
	v_mfma_f32_16x16x32_bf16 v[20:23], v[130:133], v[110:113], v[20:23]
	v_mfma_f32_16x16x32_bf16 v[16:19], v[118:121], v[114:117], v[16:19]
	v_mfma_f32_16x16x32_bf16 v[12:15], v[122:125], v[114:117], v[12:15]
	v_mfma_f32_16x16x32_bf16 v[8:11], v[126:129], v[114:117], v[8:11]
	v_mfma_f32_16x16x32_bf16 v[4:7], v[130:133], v[114:117], v[4:7]
	v_mfma_f32_16x16x32_bf16 v[64:67], v[118:121], v[80:83], v[64:67]
	v_mfma_f32_16x16x32_bf16 v[60:63], v[122:125], v[80:83], v[60:63]
	v_mfma_f32_16x16x32_bf16 v[68:71], v[130:133], v[80:83], v[52:55]
	s_setprio 0
	v_mov_b32_e32 v0, v198
	s_waitcnt vmcnt(0) lgkmcnt(0)
	s_barrier
; __device__ __forceinline__ unsigned pk2(float lo, float hi) { unsigned r; asm("v_cvt_pk_bf16_f32 %0, %1, %2" : "=v"(r) : "v"(lo), "v"(hi)); return r; }
; __device__ __forceinline__ float bflo(unsigned u) { return __uint_as_float(u << 16); }
; __device__ __forceinline__ float bfhi(unsigned u) { return __uint_as_float(u & 0xffff0000u); }
; __device__ __forceinline__ void gemm_RES(const bf16_t* A, int K, const bf16_t* Bt, const float* xin, float* xout, bf16_t* xb, float* rss, int item, char* lds) {
;     ...
; #pragma unroll
;   for (int m = 0; m < 4; m++) {
;     const int rowg = m0 + wr * 64 + m * 16 + fr;
;     const size_t ro = (size_t)rowg * DM;
;     float sq = 0.f;
; #pragma unroll
;     for (int n = 0; n < 4; n++) {
;       const int col = n0 + wc * 64 + n * 16 + fq * 4;
;       f32x4 xv = *(const f32x4*)(xin + ro + col);
;       const f32x4 xn = xv + acc[m][n];
;       *(f32x4*)(xout + ro + col) = xn;
;       u32x2 w; w[0] = pk2(xn[0], xn[1]); w[1] = pk2(xn[2], xn[3]); *(u32x2*)(xb + ro + col) = w;
;       const float b0 = bflo(w[0]), b1 = bfhi(w[0]), b2 = bflo(w[1]), b3 = bfhi(w[1]);
;       sq += b0 * b0 + b1 * b1 + b2 * b2 + b3 * b3;
;     }
;     sq += __shfl_xor(sq, 16); sq += __shfl_xor(sq, 32);
;     if (fq == 0) unsafeAtomicAdd(rss + rowg, sq);
;   }
	v_readlane_b32 s4, v252, 35
	v_ashrrev_i32_e32 v2, 1, v0
	v_and_b32_e32 v2, 0xffffffc0, v2
	v_bfe_u32 v80, v0, 4, 2
	v_add_u32_e32 v2, s3, v2
	v_and_b32_e32 v1, 64, v0
	v_and_or_b32 v0, v0, 15, v2
	v_lshlrev_b32_e32 v2, 2, v80
	v_or3_b32 v54, v2, v1, s2
	v_ashrrev_i32_e32 v1, 31, v0
	v_lshlrev_b64 v[52:53], 12, v[0:1]
	v_readlane_b32 s18, v252, 49
	v_readlane_b32 s19, v252, 50
	v_lshlrev_b32_e32 v2, 2, v54
	v_readlane_b32 s5, v252, 36
	v_lshl_add_u64 v[52:53], s[18:19], 0, v[52:53]
	v_lshl_add_u64 v[76:77], v[52:53], 0, v[2:3]
	global_load_dwordx4 v[72:75], v[76:77], off
	v_lshlrev_b32_e32 v52, 1, v54
	v_lshlrev_b64 v[54:55], 11, v[0:1]
	v_mov_b32_e32 v53, v3
	v_lshl_add_u64 v[54:55], s[26:27], 0, v[54:55]
	v_lshl_add_u64 v[78:79], v[54:55], 0, v[52:53]
	v_readlane_b32 s6, v252, 37
	v_readlane_b32 s7, v252, 38
	v_readlane_b32 s8, v252, 39
	v_readlane_b32 s9, v252, 40
	v_readlane_b32 s10, v252, 41
	v_readlane_b32 s11, v252, 42
	v_readlane_b32 s12, v252, 43
	v_readlane_b32 s13, v252, 44
	v_readlane_b32 s14, v252, 45
	v_readlane_b32 s15, v252, 46
	v_readlane_b32 s16, v252, 47
	v_readlane_b32 s17, v252, 48
	s_waitcnt vmcnt(0)
	v_pk_add_f32 v[66:67], v[66:67], v[74:75]
	v_pk_add_f32 v[64:65], v[64:65], v[72:73]
	global_store_dwordx4 v[76:77], v[64:67], off
	v_cvt_pk_bf16_f32 v54, v64, v65
	v_cvt_pk_bf16_f32 v55, v66, v67
	global_store_dwordx2 v[78:79], v[54:55], off
	global_load_dwordx4 v[64:67], v[76:77], off offset:64
	s_waitcnt vmcnt(0)
	v_pk_add_f32 v[62:63], v[62:63], v[66:67]
	v_pk_add_f32 v[60:61], v[60:61], v[64:65]
	global_store_dwordx4 v[76:77], v[60:63], off offset:64
	v_cvt_pk_bf16_f32 v64, v60, v61
	v_cvt_pk_bf16_f32 v65, v62, v63
	global_store_dwordx2 v[78:79], v[64:65], off offset:32
	global_load_dwordx4 v[60:63], v[76:77], off offset:128
	v_lshlrev_b32_e32 v66, 16, v54
	v_and_b32_e32 v54, 0xffff0000, v54
	v_mul_f32_e32 v54, v54, v54
	v_lshlrev_b32_e32 v67, 16, v55
	v_fmac_f32_e32 v54, v66, v66
	v_and_b32_e32 v55, 0xffff0000, v55
	v_fmac_f32_e32 v54, v67, v67
	v_fmac_f32_e32 v54, v55, v55
	v_lshlrev_b32_e32 v55, 16, v64
	v_and_b32_e32 v64, 0xffff0000, v64
	v_mul_f32_e32 v64, v64, v64
	v_lshlrev_b32_e32 v66, 16, v65
	v_fmac_f32_e32 v64, v55, v55
	v_and_b32_e32 v65, 0xffff0000, v65
	v_fmac_f32_e32 v64, v66, v66
	v_fmac_f32_e32 v64, v65, v65
	v_add_f32_e32 v54, v54, v64
	s_waitcnt vmcnt(0)
	v_pk_add_f32 v[58:59], v[58:59], v[62:63]
	v_pk_add_f32 v[56:57], v[56:57], v[60:61]
	global_store_dwordx4 v[76:77], v[56:59], off offset:128
	v_cvt_pk_bf16_f32 v62, v56, v57
	v_cvt_pk_bf16_f32 v63, v58, v59
	global_store_dwordx2 v[78:79], v[62:63], off offset:64
	global_load_dwordx4 v[58:61], v[76:77], off offset:192
	v_lshlrev_b32_e32 v55, 16, v62
	v_and_b32_e32 v62, 0xffff0000, v62
	v_mul_f32_e32 v62, v62, v62
	v_lshlrev_b32_e32 v64, 16, v63
	v_fmac_f32_e32 v62, v55, v55
	v_and_b32_e32 v63, 0xffff0000, v63
	v_fmac_f32_e32 v62, v64, v64
	v_fmac_f32_e32 v62, v63, v63
	v_add_f32_e32 v54, v54, v62
	v_and_b32_e32 v57, 64, v218
	v_xor_b32_e32 v56, 16, v218
	v_add_u32_e32 v57, 64, v57
	v_cmp_lt_i32_e32 vcc, v56, v57
	s_waitcnt vmcnt(0)
	v_pk_add_f32 v[58:59], v[68:69], v[58:59]
	s_nop 0
	v_cvt_pk_bf16_f32 v62, v58, v59
	v_pk_add_f32 v[60:61], v[70:71], v[60:61]
	v_and_b32_e32 v64, 0xffff0000, v62
	v_lshlrev_b32_e32 v55, 16, v62
	v_mul_f32_e32 v64, v64, v64
	v_cvt_pk_bf16_f32 v63, v60, v61
	v_fmac_f32_e32 v64, v55, v55
	v_lshlrev_b32_e32 v65, 16, v63
	v_and_b32_e32 v66, 0xffff0000, v63
	v_fmac_f32_e32 v64, v65, v65
	v_cndmask_b32_e32 v56, v218, v56, vcc
	v_fmac_f32_e32 v64, v66, v66
	v_lshlrev_b32_e32 v56, 2, v56
	v_add_f32_e32 v54, v54, v64
	ds_bpermute_b32 v55, v56, v54
	v_xor_b32_e32 v64, 32, v218
	v_cmp_lt_i32_e32 vcc, v64, v57
	global_store_dwordx4 v[76:77], v[58:61], off offset:192
	global_store_dwordx2 v[78:79], v[62:63], off offset:96
	v_cndmask_b32_e32 v57, v218, v64, vcc
	s_waitcnt lgkmcnt(0)
	v_add_f32_e32 v54, v54, v55
	v_lshlrev_b32_e32 v57, 2, v57
	ds_bpermute_b32 v55, v57, v54
	v_cmp_eq_u32_e32 vcc, 0, v80
	s_and_saveexec_b64 s[28:29], vcc
	s_cbranch_execz .LBB0_98
	v_lshl_add_u64 v[58:59], v[0:1], 2, s[24:25]
	s_waitcnt lgkmcnt(0)
	v_add_f32_e32 v1, v54, v55
	global_atomic_add_f32 v[58:59], v1, off

; __device__ __forceinline__ unsigned char* WS(const Params& p) { unsigned z = 0; asm volatile("" : "+s"(z)); return p.ws + z; }
; __device__ __forceinline__ int opaque_tid() { int t = threadIdx.x; asm volatile("" : "+v"(t)); return t; }
; __device__ __forceinline__ void gemm_mainloop_d(const bf16_t* __restrict__ Ap, int lda, const bf16_t* __restrict__ Bt, int K,
;                                                 int m0, int n0, f32x4 (&acc)[4][4], char* lds) {
;   const int tid = opaque_tid(), lane = tid & 63, wid = tid >> 6, wr = wid >> 1, wc = wid & 1, fr = lane & 15, fq = lane >> 4;
; #pragma unroll
;   for (int m = 0; m < 4; m++)
; #pragma unroll
;     for (int n = 0; n < 4; n++) acc[m][n] = (f32x4){0.f, 0.f, 0.f, 0.f};
;   const int nk = K >> 6;
;   const int lrow = tid >> 3, cph = tid & 7;
;   auto dma = [&](int kt, int st) {
;     char* la = lds + st * 32768; char* lb = la + 16384;
; #pragma unroll
;     for (int i = 0; i < 4; i++) {
;       const int row = i * 32 + lrow; const int c = cph ^ ((row >> 1) & 7);
;       __builtin_amdgcn_global_load_lds((const unsigned*)(Ap + (size_t)(m0 + row) * lda + kt * 64 + c * 8), (__attribute__((address_space(3))) unsigned*)(la + i * 4096 + tid * 16), 16, 0, 0);
;       __builtin_amdgcn_global_load_lds((const unsigned*)(Bt + (size_t)(n0 + row) * K + kt * 64 + c * 8), (__attribute__((address_space(3))) unsigned*)(lb + i * 4096 + tid * 16), 16, 0, 0);
;     }
;   };
;   dma(0, 0);
;   asm volatile("s_waitcnt vmcnt(0)" ::: "memory"); __builtin_amdgcn_s_barrier(); asm volatile("" ::: "memory");
; __device__ __forceinline__ void gemm_GU(const Params& p, int item, char* lds) {
;   const int r_ = item >> 9, x_ = item & 7, y_ = (item >> 3) & 63;
;   const int pid = (r_ * 8 + x_) * 2 + (y_ >> 5), t32 = y_ & 31;
;   const int mt = (pid / 11) * 8 + (t32 >> 2), nt = (pid % 11) * 4 + (t32 & 3); const int m0 = mt * 128, n0 = nt * 128;
;   f32x4 acc[4][4];
;   gemm_mainloop_d((const bf16_t*)(WS(p) + OFF_XB), DM, (const bf16_t*)(WS(p) + OFF_WGU), DM, m0, n0, acc, lds);
.LBB0_108:
	s_ashr_i32 s25, s30, 6
	s_and_b32 s24, s30, 7
	s_and_b32 s25, s25, 0x7ffffff8
	s_or_b32 s24, s25, s24
	s_lshl_b32 s24, s24, 1
	s_bfe_u32 s25, s30, 0x10008
	s_or_b32 s38, s24, s25
	s_mul_hi_i32 s24, s38, 0x2e8ba2e9
	s_lshr_b32 s25, s24, 31
	s_ashr_i32 s24, s24, 1
	s_add_i32 s39, s24, s25
	s_mul_i32 s24, s39, 11
	s_sub_i32 s25, s38, s24
	s_lshl_b32 s24, s30, 2
	s_lshl_b32 s26, s30, 4
	s_lshl_b32 s40, s39, 10
	s_and_b32 s24, s24, 0x380
	s_lshl_b32 s25, s25, 9
	s_and_b32 s26, s26, 0x180
	s_and_b32 s36, s29, 0x380
	s_and_b32 s37, s28, 0x180
	s_or_b32 s24, s40, s24
	s_or_b32 s31, s25, s26
	s_mov_b32 s41, 0
	s_mov_b32 s42, 0
	s_waitcnt vmcnt(5)
	v_mov_b32_e32 v4, v198
	s_add_u32 s26, s46, s41
	s_addc_u32 s27, s47, 0
	v_ashrrev_i32_e32 v7, 3, v4
	v_lshrrev_b32_e32 v8, 1, v7
	s_waitcnt vmcnt(4)
	v_add_u32_e32 v0, s24, v7
	s_add_u32 s34, s26, 0x65a8000
	v_xor_b32_e32 v2, v8, v4
	v_ashrrev_i32_e32 v1, 31, v0
	s_addc_u32 s35, s27, 0
	v_lshlrev_b64 v[0:1], 11, v[0:1]
	v_lshlrev_b32_e32 v2, 4, v2
	v_lshl_add_u32 v82, v4, 4, 0
	v_lshl_add_u64 v[0:1], s[34:35], 0, v[0:1]
	v_and_b32_e32 v2, 0x70, v2
	v_readfirstlane_b32 s43, v82
	s_add_u32 s26, s46, s42
	v_lshl_add_u64 v[0:1], v[0:1], 0, v[2:3]
	s_mov_b32 m0, s43
	s_addc_u32 s27, s47, 0
	global_load_lds_dwordx4 v[0:1], off
	v_add_u32_e32 v0, s31, v7
	s_add_u32 s26, s26, 0xe8cc000
	v_ashrrev_i32_e32 v1, 31, v0
	s_addc_u32 s27, s27, 0
	v_lshlrev_b64 v[0:1], 11, v[0:1]
	v_add_u32_e32 v9, 0x4000, v82
	v_lshl_add_u64 v[0:1], s[26:27], 0, v[0:1]
	v_readfirstlane_b32 s43, v9
	v_lshl_add_u64 v[0:1], v[0:1], 0, v[2:3]
	s_mov_b32 m0, s43
	v_add_u32_e32 v9, 32, v7
	global_load_lds_dwordx4 v[0:1], off
	v_add_u32_e32 v0, s24, v9
	v_ashrrev_i32_e32 v1, 31, v0
	v_lshlrev_b64 v[0:1], 11, v[0:1]
	v_add_u32_e32 v10, 0x1000, v82
	v_lshl_add_u64 v[0:1], s[34:35], 0, v[0:1]
	v_readfirstlane_b32 s43, v10
	v_lshl_add_u64 v[0:1], v[0:1], 0, v[2:3]
	s_mov_b32 m0, s43
	v_add_u32_e32 v10, 0x5000, v82
	global_load_lds_dwordx4 v[0:1], off
	v_add_u32_e32 v0, s31, v9
	v_ashrrev_i32_e32 v1, 31, v0
	v_lshlrev_b64 v[0:1], 11, v[0:1]
	v_lshl_add_u64 v[0:1], s[26:27], 0, v[0:1]
	v_readfirstlane_b32 s43, v10
	v_lshl_add_u64 v[0:1], v[0:1], 0, v[2:3]
	s_mov_b32 m0, s43
	v_add_u32_e32 v10, 64, v7
	global_load_lds_dwordx4 v[0:1], off
	v_add_u32_e32 v0, s24, v10
	v_ashrrev_i32_e32 v1, 31, v0
	v_lshlrev_b64 v[0:1], 11, v[0:1]
	v_add_u32_e32 v11, 0x2000, v82
	v_lshl_add_u64 v[0:1], s[34:35], 0, v[0:1]
	v_readfirstlane_b32 s43, v11
	v_lshl_add_u64 v[0:1], v[0:1], 0, v[2:3]
	s_mov_b32 m0, s43
	v_add_u32_e32 v11, 0x6000, v82
	global_load_lds_dwordx4 v[0:1], off
	v_add_u32_e32 v0, s31, v10
	v_ashrrev_i32_e32 v1, 31, v0
	v_lshlrev_b64 v[0:1], 11, v[0:1]
	v_lshl_add_u64 v[0:1], s[26:27], 0, v[0:1]
	v_readfirstlane_b32 s43, v11
	v_lshl_add_u64 v[0:1], v[0:1], 0, v[2:3]
	s_mov_b32 m0, s43
	v_add_u32_e32 v11, 0x60, v7
	global_load_lds_dwordx4 v[0:1], off
	v_add_u32_e32 v0, s24, v11
	v_ashrrev_i32_e32 v1, 31, v0
	v_lshlrev_b64 v[0:1], 11, v[0:1]
	v_add_u32_e32 v12, 0x3000, v82
	v_lshl_add_u64 v[0:1], s[34:35], 0, v[0:1]
	v_readfirstlane_b32 s34, v12
	v_lshl_add_u64 v[0:1], v[0:1], 0, v[2:3]
	s_mov_b32 m0, s34
	s_mov_b32 s4, 0x1ffffc0
	global_load_lds_dwordx4 v[0:1], off
	v_add_u32_e32 v0, s31, v11
	v_ashrrev_i32_e32 v1, 31, v0
	v_lshlrev_b64 v[0:1], 11, v[0:1]
	v_lshl_add_u64 v[0:1], s[26:27], 0, v[0:1]
	v_lshl_add_u64 v[0:1], v[0:1], 0, v[2:3]
	v_add_u32_e32 v2, 0x7000, v82
	s_or_b32 s36, s36, s40
	v_readfirstlane_b32 s26, v2
	s_mov_b32 m0, s26
	v_lshrrev_b32_e32 v5, 4, v4
	global_load_lds_dwordx4 v[0:1], off
	v_and_b32_e32 v0, 15, v4
	v_lshrrev_b32_e32 v1, 1, v4
	v_and_or_b32 v0, v1, s4, v0
	v_readlane_b32 s4, v254, 44
	s_add_u32 s26, s4, s41
	v_readlane_b32 s4, v254, 45
	s_addc_u32 s27, s4, 0
	s_lshl_b32 s34, s38, 9
	v_bfe_u32 v6, v4, 4, 2
	v_bfe_u32 v1, v4, 1, 3
	v_lshlrev_b32_e32 v2, 7, v4
	v_bitop3_b32 v4, v8, 7, v4 bitop3:0x48
	s_or_b32 s37, s37, s34
	v_bitop3_b32 v5, v5, v1, 3 bitop3:0x6c
	v_bitop3_b32 v1, v6, v1, 4 bitop3:0x36
	v_lshlrev_b32_e32 v6, 4, v4
	v_add_u32_e32 v4, s37, v7
	s_mulk_i32 s39, 0x1600
	v_and_b32_e32 v2, 0x2780, v2
	v_lshlrev_b32_e32 v5, 4, v5
	v_lshlrev_b32_e32 v0, 7, v0
	v_subrev_u32_e32 v4, s39, v4
	v_or_b32_e32 v85, v0, v5
	v_or_b32_e32 v84, v5, v2
	v_ashrrev_i32_e32 v5, 31, v4
	v_readlane_b32 s4, v254, 47
	v_lshlrev_b64 v[4:5], 11, v[4:5]
	s_add_u32 s34, s4, s42
	v_readlane_b32 s4, v254, 48
	v_or_b32_e32 v4, v4, v6
	s_addc_u32 s35, s4, 0
	s_waitcnt vmcnt(0)
	v_lshl_add_u64 v[68:69], s[34:35], 0, v[4:5]
	v_add_u32_e32 v4, s36, v9
	v_ashrrev_i32_e32 v5, 31, v4
	v_lshlrev_b64 v[4:5], 11, v[4:5]
	v_or_b32_e32 v4, v4, v6
	v_lshl_add_u64 v[70:71], s[26:27], 0, v[4:5]
	v_add_u32_e32 v4, s37, v9
	v_subrev_u32_e32 v4, s39, v4
	v_ashrrev_i32_e32 v5, 31, v4
	v_lshlrev_b64 v[4:5], 11, v[4:5]
	v_or_b32_e32 v4, v4, v6
	v_lshl_add_u64 v[72:73], s[34:35], 0, v[4:5]
	v_add_u32_e32 v4, s36, v10
	v_ashrrev_i32_e32 v5, 31, v4
	v_lshlrev_b64 v[4:5], 11, v[4:5]
	v_or_b32_e32 v4, v4, v6
	v_lshl_add_u64 v[74:75], s[26:27], 0, v[4:5]
	v_add_u32_e32 v4, s37, v10
	v_subrev_u32_e32 v4, s39, v4
	v_ashrrev_i32_e32 v5, 31, v4
	v_lshlrev_b64 v[4:5], 11, v[4:5]
	v_or_b32_e32 v4, v4, v6
	v_lshl_add_u64 v[76:77], s[34:35], 0, v[4:5]
	v_add_u32_e32 v4, s36, v11
	v_ashrrev_i32_e32 v5, 31, v4
	v_lshlrev_b64 v[4:5], 11, v[4:5]
	v_or_b32_e32 v4, v4, v6
	v_lshl_add_u64 v[78:79], s[26:27], 0, v[4:5]
	v_add_u32_e32 v4, s37, v11
	v_lshlrev_b32_e32 v1, 4, v1
	v_subrev_u32_e32 v4, s39, v4
	v_or_b32_e32 v83, v1, v0
	v_add_u32_e32 v0, s36, v7
	v_ashrrev_i32_e32 v5, 31, v4
	v_or_b32_e32 v2, v1, v2
	v_ashrrev_i32_e32 v1, 31, v0
	v_lshlrev_b64 v[4:5], 11, v[4:5]
	s_waitcnt vmcnt(0)
	s_barrier
; __device__ __forceinline__ void gemm_mainloop_d(const bf16_t* __restrict__ Ap, int lda, const bf16_t* __restrict__ Bt, int K,
;                                                 int m0, int n0, f32x4 (&acc)[4][4], char* lds) {
;     ...
; #pragma unroll
;   for (int m = 0; m < 4; m++)
; #pragma unroll
;     for (int n = 0; n < 4; n++) acc[m][n] = (f32x4){0.f, 0.f, 0.f, 0.f};
;   const int nk = K >> 6;
;   const int lrow = tid >> 3, cph = tid & 7;
;   auto dma = [&](int kt, int st) {
;     char* la = lds + st * 32768; char* lb = la + 16384;
; #pragma unroll
;     for (int i = 0; i < 4; i++) {
;       const int row = i * 32 + lrow; const int c = cph ^ ((row >> 1) & 7);
;       __builtin_amdgcn_global_load_lds((const unsigned*)(Ap + (size_t)(m0 + row) * lda + kt * 64 + c * 8), (__attribute__((address_space(3))) unsigned*)(la + i * 4096 + tid * 16), 16, 0, 0);
;       __builtin_amdgcn_global_load_lds((const unsigned*)(Bt + (size_t)(n0 + row) * K + kt * 64 + c * 8), (__attribute__((address_space(3))) unsigned*)(lb + i * 4096 + tid * 16), 16, 0, 0);
;     }
;   };
;   dma(0, 0);
;   asm volatile("s_waitcnt vmcnt(0)" ::: "memory"); __builtin_amdgcn_s_barrier(); asm volatile("" ::: "memory");
;   for (int kt = 0; kt < nk; kt++) {
;     const int st = kt & 1;
;     if (kt + 1 < nk) dma(kt + 1, st ^ 1);
;     const char* la = lds + st * 32768; const char* lb = la + 16384;
;     bf16x8 af[2][4], bfv[2][4];
; #pragma unroll
;     for (int kc = 0; kc < 2; kc++) {
; #pragma unroll
;       for (int m = 0; m < 4; m++) { const int row = wr * 64 + m * 16 + fr; af[kc][m] = *(const bf16x8*)(la + (row * 8 + ((kc * 4 + fq) ^ ((row >> 1) & 7))) * 16); }
; #pragma unroll
;       for (int n = 0; n < 4; n++) { const int row = wc * 64 + n * 16 + fr; bfv[kc][n] = *(const bf16x8*)(lb + (row * 8 + ((kc * 4 + fq) ^ ((row >> 1) & 7))) * 16); }
;     }
;     __builtin_amdgcn_s_setprio(1);
; #pragma unroll
;     for (int kc = 0; kc < 2; kc++)
; #pragma unroll
;       for (int m = 0; m < 4; m++)
; #pragma unroll
;         for (int n = 0; n < 4; n++) acc[m][n] = __builtin_amdgcn_mfma_f32_16x16x32_bf16(bfv[kc][n], af[kc][m], acc[m][n], 0, 0, 0);
;     __builtin_amdgcn_s_setprio(0);
;     asm volatile("s_waitcnt vmcnt(0) lgkmcnt(0)" ::: "memory"); __builtin_amdgcn_s_barrier(); asm volatile("" ::: "memory");
;   }
	v_lshlrev_b64 v[0:1], 11, v[0:1]
	v_or_b32_e32 v4, v4, v6
	v_or_b32_e32 v0, v0, v6
	v_lshl_add_u64 v[80:81], s[34:35], 0, v[4:5]
	v_mov_b32_e32 v4, 0
	s_mov_b32 s25, 0
	v_lshl_add_u64 v[0:1], s[26:27], 0, v[0:1]
	s_mov_b64 s[26:27], 0
	v_mov_b32_e32 v5, v4
	v_mov_b32_e32 v6, v4
	v_mov_b32_e32 v7, v4
	v_mov_b32_e32 v8, v4
	v_mov_b32_e32 v9, v4
	v_mov_b32_e32 v10, v4
	v_mov_b32_e32 v11, v4
	v_mov_b32_e32 v12, v4
	v_mov_b32_e32 v13, v4
	v_mov_b32_e32 v14, v4
	v_mov_b32_e32 v15, v4
	v_mov_b32_e32 v16, v4
	v_mov_b32_e32 v17, v4
	v_mov_b32_e32 v18, v4
	v_mov_b32_e32 v19, v4
	v_mov_b32_e32 v20, v4
	v_mov_b32_e32 v21, v4
	v_mov_b32_e32 v22, v4
	v_mov_b32_e32 v23, v4
	v_mov_b32_e32 v24, v4
	v_mov_b32_e32 v25, v4
	v_mov_b32_e32 v26, v4
	v_mov_b32_e32 v27, v4
	v_mov_b32_e32 v28, v4
	v_mov_b32_e32 v29, v4
	v_mov_b32_e32 v30, v4
	v_mov_b32_e32 v31, v4
	v_mov_b32_e32 v32, v4
	v_mov_b32_e32 v33, v4
	v_mov_b32_e32 v34, v4
	v_mov_b32_e32 v35, v4
	v_mov_b32_e32 v36, v4
	v_mov_b32_e32 v37, v4
	v_mov_b32_e32 v38, v4
	v_mov_b32_e32 v39, v4
	v_mov_b32_e32 v40, v4
	v_mov_b32_e32 v41, v4
	v_mov_b32_e32 v42, v4
	v_mov_b32_e32 v43, v4
	v_mov_b32_e32 v44, v4
	v_mov_b32_e32 v45, v4
	v_mov_b32_e32 v46, v4
	v_mov_b32_e32 v47, v4
	v_mov_b32_e32 v48, v4
	v_mov_b32_e32 v49, v4
	v_mov_b32_e32 v50, v4
	v_mov_b32_e32 v51, v4
	v_mov_b32_e32 v52, v4
	v_mov_b32_e32 v53, v4
	v_mov_b32_e32 v54, v4
	v_mov_b32_e32 v55, v4
	v_mov_b32_e32 v56, v4
	v_mov_b32_e32 v57, v4
	v_mov_b32_e32 v58, v4
	v_mov_b32_e32 v59, v4
	v_mov_b32_e32 v60, v4
	v_mov_b32_e32 v61, v4
	v_mov_b32_e32 v62, v4
	v_mov_b32_e32 v63, v4
	v_mov_b32_e32 v64, v4
	v_mov_b32_e32 v65, v4
	v_mov_b32_e32 v66, v4
	v_mov_b32_e32 v67, v4
	v_subrev_u32_e32 v150, s46, v0
	v_subrev_u32_e32 v151, s46, v68
	v_subrev_u32_e32 v152, s46, v70
	v_subrev_u32_e32 v153, s46, v72
	v_subrev_u32_e32 v154, s46, v74
	v_subrev_u32_e32 v155, s46, v76
	v_subrev_u32_e32 v156, s46, v78
	v_subrev_u32_e32 v157, s46, v80
	v_readfirstlane_b32 vcc_hi, v82
.LBB0_109:
	s_and_b32 s34, s25, 0x8000
	s_xor_b32 s35, s34, 0x8000
	s_add_i32 s35, s35, vcc_hi
	s_mov_b32 m0, s35
	s_add_i32 vcc_lo, s35, 0x4000
	global_load_lds_dwordx4 v150, s[46:47]
	s_mov_b32 m0, vcc_lo
	s_add_i32 vcc_lo, s35, 0x1000
	global_load_lds_dwordx4 v151, s[46:47]
	s_mov_b32 m0, vcc_lo
	s_add_i32 vcc_lo, s35, 0x5000
	global_load_lds_dwordx4 v152, s[46:47]
	s_mov_b32 m0, vcc_lo
	s_add_i32 vcc_lo, s35, 0x2000
	global_load_lds_dwordx4 v153, s[46:47]
	s_mov_b32 m0, vcc_lo
	s_add_i32 vcc_lo, s35, 0x6000
	global_load_lds_dwordx4 v154, s[46:47]
	s_mov_b32 m0, vcc_lo
	s_add_i32 vcc_lo, s35, 0x3000
	global_load_lds_dwordx4 v155, s[46:47]
	s_mov_b32 m0, vcc_lo
	s_add_i32 vcc_lo, s35, 0x7000
	global_load_lds_dwordx4 v156, s[46:47]
	s_mov_b32 m0, vcc_lo
	s_nop 0
	global_load_lds_dwordx4 v157, s[46:47]
	v_add_u32_e32 v150, 0x80, v150
	v_add_u32_e32 v151, 0x80, v151
	v_add_u32_e32 v152, 0x80, v152
	v_add_u32_e32 v153, 0x80, v153
	v_add_u32_e32 v154, 0x80, v154
	v_add_u32_e32 v155, 0x80, v155
	v_add_u32_e32 v156, 0x80, v156
	v_add_u32_e32 v157, 0x80, v157
	v_add_u32_e32 v98, s34, v85
	v_add_u32_e32 v114, s34, v84
	v_add_u32_e32 v130, s34, v83
	v_add_u32_e32 v146, s34, v2
	ds_read_b128 v[86:89], v98
	ds_read_b128 v[90:93], v98 offset:2048
	ds_read_b128 v[94:97], v98 offset:4096
	ds_read_b128 v[98:101], v98 offset:6144
	ds_read_b128 v[102:105], v114 offset:16384
	ds_read_b128 v[106:109], v114 offset:18432
	ds_read_b128 v[110:113], v114 offset:20480
	ds_read_b128 v[114:117], v114 offset:22528
	ds_read_b128 v[118:121], v130
	ds_read_b128 v[122:125], v130 offset:2048
	ds_read_b128 v[126:129], v130 offset:4096
	ds_read_b128 v[130:133], v130 offset:6144
	ds_read_b128 v[134:137], v146 offset:16384
	ds_read_b128 v[138:141], v146 offset:18432
	ds_read_b128 v[142:145], v146 offset:20480
	ds_read_b128 v[146:149], v146 offset:22528
	s_setprio 1
	s_waitcnt lgkmcnt(0)
	v_mfma_f32_16x16x32_bf16 v[64:67], v[102:105], v[86:89], v[64:67]
	v_mfma_f32_16x16x32_bf16 v[60:63], v[106:109], v[86:89], v[60:63]
	v_mfma_f32_16x16x32_bf16 v[56:59], v[110:113], v[86:89], v[56:59]
	v_mfma_f32_16x16x32_bf16 v[52:55], v[114:117], v[86:89], v[52:55]
	v_mfma_f32_16x16x32_bf16 v[48:51], v[102:105], v[90:93], v[48:51]
	v_mfma_f32_16x16x32_bf16 v[44:47], v[106:109], v[90:93], v[44:47]
	v_mfma_f32_16x16x32_bf16 v[40:43], v[110:113], v[90:93], v[40:43]
	v_mfma_f32_16x16x32_bf16 v[36:39], v[114:117], v[90:93], v[36:39]
	v_mfma_f32_16x16x32_bf16 v[32:35], v[102:105], v[94:97], v[32:35]
	v_mfma_f32_16x16x32_bf16 v[28:31], v[106:109], v[94:97], v[28:31]
	v_mfma_f32_16x16x32_bf16 v[24:27], v[110:113], v[94:97], v[24:27]
	v_mfma_f32_16x16x32_bf16 v[20:23], v[114:117], v[94:97], v[20:23]
	v_mfma_f32_16x16x32_bf16 v[16:19], v[102:105], v[98:101], v[16:19]
	v_mfma_f32_16x16x32_bf16 v[12:15], v[106:109], v[98:101], v[12:15]
	v_mfma_f32_16x16x32_bf16 v[8:11], v[110:113], v[98:101], v[8:11]
	v_mfma_f32_16x16x32_bf16 v[4:7], v[114:117], v[98:101], v[4:7]
	v_mfma_f32_16x16x32_bf16 v[64:67], v[134:137], v[118:121], v[64:67]
	v_mfma_f32_16x16x32_bf16 v[60:63], v[138:141], v[118:121], v[60:63]
	v_mfma_f32_16x16x32_bf16 v[56:59], v[142:145], v[118:121], v[56:59]
	v_mfma_f32_16x16x32_bf16 v[52:55], v[146:149], v[118:121], v[52:55]
	v_mfma_f32_16x16x32_bf16 v[48:51], v[134:137], v[122:125], v[48:51]
	v_mfma_f32_16x16x32_bf16 v[44:47], v[138:141], v[122:125], v[44:47]
	v_mfma_f32_16x16x32_bf16 v[40:43], v[142:145], v[122:125], v[40:43]
	v_mfma_f32_16x16x32_bf16 v[36:39], v[146:149], v[122:125], v[36:39]
	v_mfma_f32_16x16x32_bf16 v[32:35], v[134:137], v[126:129], v[32:35]
	v_mfma_f32_16x16x32_bf16 v[28:31], v[138:141], v[126:129], v[28:31]
	v_mfma_f32_16x16x32_bf16 v[24:27], v[142:145], v[126:129], v[24:27]
	v_mfma_f32_16x16x32_bf16 v[20:23], v[146:149], v[126:129], v[20:23]
	v_mfma_f32_16x16x32_bf16 v[16:19], v[134:137], v[130:133], v[16:19]
	v_mfma_f32_16x16x32_bf16 v[12:15], v[138:141], v[130:133], v[12:15]
	v_mfma_f32_16x16x32_bf16 v[8:11], v[142:145], v[130:133], v[8:11]
	v_mfma_f32_16x16x32_bf16 v[4:7], v[146:149], v[130:133], v[4:7]
	s_setprio 0
	s_waitcnt vmcnt(0) lgkmcnt(0)
	s_barrier
; __device__ __forceinline__ unsigned char* WS(const Params& p) { unsigned z = 0; asm volatile("" : "+s"(z)); return p.ws + z; }
; __device__ __forceinline__ void gemm_mainloop_d(const bf16_t* __restrict__ Ap, int lda, const bf16_t* __restrict__ Bt, int K,
;                                                 int m0, int n0, f32x4 (&acc)[4][4], char* lds) {
;     ...
;   for (int kt = 0; kt < nk; kt++) {
;     const int st = kt & 1;
;     if (kt + 1 < nk) dma(kt + 1, st ^ 1);
;     const char* la = lds + st * 32768; const char* lb = la + 16384;
;     bf16x8 af[2][4], bfv[2][4];
; #pragma unroll
;     for (int kc = 0; kc < 2; kc++) {
; #pragma unroll
;       for (int m = 0; m < 4; m++) { const int row = wr * 64 + m * 16 + fr; af[kc][m] = *(const bf16x8*)(la + (row * 8 + ((kc * 4 + fq) ^ ((row >> 1) & 7))) * 16); }
; #pragma unroll
;       for (int n = 0; n < 4; n++) { const int row = wc * 64 + n * 16 + fr; bfv[kc][n] = *(const bf16x8*)(lb + (row * 8 + ((kc * 4 + fq) ^ ((row >> 1) & 7))) * 16); }
;     }
;     __builtin_amdgcn_s_setprio(1);
; #pragma unroll
;     for (int kc = 0; kc < 2; kc++)
; #pragma unroll
;       for (int m = 0; m < 4; m++)
; #pragma unroll
;         for (int n = 0; n < 4; n++) acc[m][n] = __builtin_amdgcn_mfma_f32_16x16x32_bf16(bfv[kc][n], af[kc][m], acc[m][n], 0, 0, 0);
;     __builtin_amdgcn_s_setprio(0);
;     asm volatile("s_waitcnt vmcnt(0) lgkmcnt(0)" ::: "memory"); __builtin_amdgcn_s_barrier(); asm volatile("" ::: "memory");
;   }
; __device__ __forceinline__ void gemm_GU(const Params& p, int item, char* lds) {
;     ...
;   const float* rssg = (const float*)(WS(p) + OFF_RSS) + T + m0;
;   bf16_t* U = (bf16_t*)(WS(p) + OFF_U);
; #pragma unroll
;   for (int m = 0; m < 4; m++) {
;     const int rl = wr * 64 + m * 16 + fr; const float r = rsqrtf(rssg[rl] * (1.f / 1024.f) + 1e-6f);
	s_add_u32 s26, s26, 0x80
	s_addc_u32 s27, s27, 0
	s_add_i32 s25, s25, 0x8000
	s_cmpk_lg_i32 s26, 0x780
	s_cbranch_scc1 .LBB0_109
	v_add_u32_e32 v0, 0, v85
	ds_read_b128 v[68:71], v0 offset:32768
	ds_read_b128 v[72:75], v0 offset:34816
	ds_read_b128 v[76:79], v0 offset:36864
	ds_read_b128 v[86:89], v0 offset:38912
	v_add_u32_e32 v0, 0, v84
	ds_read_b128 v[90:93], v0 offset:49152
	ds_read_b128 v[94:97], v0 offset:51200
	ds_read_b128 v[98:101], v0 offset:53248
	ds_read_b128 v[102:105], v0 offset:55296
	v_add_u32_e32 v0, 0, v83
	ds_read_b128 v[80:83], v0 offset:32768
	ds_read_b128 v[106:109], v0 offset:34816
	ds_read_b128 v[110:113], v0 offset:36864
	ds_read_b128 v[114:117], v0 offset:38912
	v_add_u32_e32 v0, 0, v2
	ds_read_b128 v[118:121], v0 offset:49152
	ds_read_b128 v[122:125], v0 offset:51200
	ds_read_b128 v[126:129], v0 offset:53248
	ds_read_b128 v[130:133], v0 offset:55296
	s_setprio 1
	s_waitcnt lgkmcnt(0)
	v_mfma_f32_16x16x32_bf16 v[64:67], v[90:93], v[68:71], v[64:67]
	v_mfma_f32_16x16x32_bf16 v[60:63], v[94:97], v[68:71], v[60:63]
	v_mfma_f32_16x16x32_bf16 v[56:59], v[98:101], v[68:71], v[56:59]
	v_mfma_f32_16x16x32_bf16 v[52:55], v[102:105], v[68:71], v[52:55]
	v_mfma_f32_16x16x32_bf16 v[48:51], v[90:93], v[72:75], v[48:51]
	v_mfma_f32_16x16x32_bf16 v[44:47], v[94:97], v[72:75], v[44:47]
	v_mfma_f32_16x16x32_bf16 v[68:71], v[98:101], v[72:75], v[40:43]
	v_mfma_f32_16x16x32_bf16 v[72:75], v[102:105], v[72:75], v[36:39]
	v_mfma_f32_16x16x32_bf16 v[32:35], v[90:93], v[76:79], v[32:35]
	v_mfma_f32_16x16x32_bf16 v[28:31], v[94:97], v[76:79], v[28:31]
	v_mfma_f32_16x16x32_bf16 v[134:137], v[98:101], v[76:79], v[24:27]
	v_mfma_f32_16x16x32_bf16 v[76:79], v[102:105], v[76:79], v[20:23]
	v_mfma_f32_16x16x32_bf16 v[16:19], v[90:93], v[86:89], v[16:19]
	v_mfma_f32_16x16x32_bf16 v[12:15], v[94:97], v[86:89], v[12:15]
	v_mfma_f32_16x16x32_bf16 v[90:93], v[98:101], v[86:89], v[8:11]
	v_mfma_f32_16x16x32_bf16 v[84:87], v[102:105], v[86:89], v[4:7]
	v_mfma_f32_16x16x32_bf16 v[64:67], v[118:121], v[80:83], v[64:67]
	v_mfma_f32_16x16x32_bf16 v[60:63], v[122:125], v[80:83], v[60:63]
	v_mfma_f32_16x16x32_bf16 v[56:59], v[126:129], v[80:83], v[56:59]
	v_mfma_f32_16x16x32_bf16 v[52:55], v[130:133], v[80:83], v[52:55]
	v_mfma_f32_16x16x32_bf16 v[40:43], v[118:121], v[106:109], v[48:51]
	v_mfma_f32_16x16x32_bf16 v[48:51], v[122:125], v[106:109], v[44:47]
	v_mfma_f32_16x16x32_bf16 v[36:39], v[126:129], v[106:109], v[68:71]
	v_mfma_f32_16x16x32_bf16 v[44:47], v[130:133], v[106:109], v[72:75]
	v_mfma_f32_16x16x32_bf16 v[24:27], v[118:121], v[110:113], v[32:35]
	v_mfma_f32_16x16x32_bf16 v[32:35], v[122:125], v[110:113], v[28:31]
	v_mfma_f32_16x16x32_bf16 v[20:23], v[126:129], v[110:113], v[134:137]
	v_mfma_f32_16x16x32_bf16 v[28:31], v[130:133], v[110:113], v[76:79]
	v_mfma_f32_16x16x32_bf16 v[8:11], v[118:121], v[114:117], v[16:19]
	v_mfma_f32_16x16x32_bf16 v[16:19], v[122:125], v[114:117], v[12:15]
	v_mfma_f32_16x16x32_bf16 v[4:7], v[126:129], v[114:117], v[90:93]
	v_mfma_f32_16x16x32_bf16 v[12:15], v[130:133], v[114:117], v[84:87]
	s_setprio 0
	v_mov_b32_e32 v2, v198
	s_mov_b32 s25, s89
	s_waitcnt vmcnt(0) lgkmcnt(0)
	s_barrier
	s_add_u32 s34, s46, s25
	s_addc_u32 s35, s47, 0
	s_ashr_i32 s25, s24, 31
	v_and_b32_e32 v0, 15, v2
	s_lshl_b64 s[26:27], s[24:25], 2
	v_ashrrev_i32_e32 v1, 1, v2
	s_movk_i32 s4, 0xffc0
	s_add_u32 s26, s34, s26
	v_and_or_b32 v0, v1, s4, v0
	s_addc_u32 s27, s35, s27
	v_ashrrev_i32_e32 v1, 31, v0
	v_lshl_add_u64 v[68:69], v[0:1], 2, s[26:27]
	s_mov_b32 s26, 0xff9c000
	v_add_co_u32_e32 v70, vcc, s26, v68
	s_mov_b32 s25, s89
	s_nop 0
	v_addc_co_u32_e32 v71, vcc, 0, v69, vcc
	global_load_dword v74, v[70:71], off
	v_mov_b32_e32 v71, v64
	v_mov_b32_e32 v64, v61
	v_mov_b32_e32 v61, v66
	v_mov_b32_e32 v66, v63
	v_mov_b32_e32 v63, v56
	v_mov_b32_e32 v56, v53
	v_mov_b32_e32 v70, v60
	v_mov_b32_e32 v60, v62
	v_mov_b32_e32 v62, v52
	v_mov_b32_e32 v72, v54
	v_mov_b32_e32 v73, v58
	v_mov_b32_e32 v58, v55
	v_lshrrev_b32_e32 v1, 1, v2
	v_lshrrev_b32_e32 v2, 2, v2
	s_add_u32 s26, s46, s25
	v_and_b32_e32 v52, 12, v2
	v_add_u32_e32 v2, s24, v0
	s_addc_u32 s27, s47, 0
	s_mov_b64 s[24:25], 0xff9c000
	v_lshl_add_u64 v[54:55], v[68:69], 0, s[24:25]
	s_add_u32 s24, s26, 0x768000
	v_and_b32_e32 v1, 32, v1
	s_addc_u32 s25, s27, 0
	s_ashr_i32 s26, s31, 1
	v_or3_b32 v52, v1, s26, v52
	v_mov_b64_e32 v[0:1], s[24:25]
	v_mad_i64_i32 v[68:69], s[24:25], v2, s33, v[0:1]
	s_add_i32 s30, s30, s77
	s_add_i32 s29, s29, s2
	s_add_i32 s28, s28, s3
	s_cmpk_gt_i32 s30, 0x15ff
	s_waitcnt vmcnt(0)
; __device__ __forceinline__ unsigned pk2(float lo, float hi) { unsigned r; asm("v_cvt_pk_bf16_f32 %0, %1, %2" : "=v"(r) : "v"(lo), "v"(hi)); return r; }
; __device__ __forceinline__ float sigmoidf_(float x) { return __builtin_amdgcn_rcpf(1.0f + __expf(-x)); }
; __device__ __forceinline__ void gemm_GU(const Params& p, int item, char* lds) {
;     ...
;   for (int m = 0; m < 4; m++) {
;     const int rl = wr * 64 + m * 16 + fr; const float r = rsqrtf(rssg[rl] * (1.f / 1024.f) + 1e-6f);
; #pragma unroll
;     for (int i = 0; i < 2; i++) {
;       f32x4 g = acc[m][2 * i] * r, u = acc[m][2 * i + 1] * r, o;
; #pragma unroll
;       for (int j = 0; j < 4; j++) o[j] = g[j] * sigmoidf_(g[j]) * u[j];
;       const int col = (n0 >> 1) + wc * 32 + i * 16 + fq * 4;
;       u32x2 w; w[0] = pk2(o[0], o[1]); w[1] = pk2(o[2], o[3]);
;       *(u32x2*)(U + (size_t)(m0 + rl) * DFF + col) = w;
;     }
;   }
	v_fmamk_f32 v53, v74, 0x3a800000, v200
	v_mul_f32_e32 v74, 0x4b800000, v53
	v_cmp_gt_f32_e32 vcc, s83, v53
	s_nop 1
	v_cndmask_b32_e32 v53, v53, v74, vcc
	v_rsq_f32_e32 v74, v53
	v_ashrrev_i32_e32 v53, 31, v52
	v_lshlrev_b64 v[52:53], 1, v[52:53]
	v_lshl_add_u64 v[68:69], v[68:69], 0, v[52:53]
	v_mul_f32_e32 v75, 0x45800000, v74
	v_cndmask_b32_e32 v74, v74, v75, vcc
	v_pk_mul_f32 v[60:61], v[60:61], v[74:75] op_sel_hi:[1,0]
	v_pk_mul_f32 v[70:71], v[70:71], v[74:75] op_sel_hi:[1,0]
	v_pk_mul_f32 v[64:65], v[64:65], v[74:75] op_sel_hi:[1,0]
	v_pk_mul_f32 v[66:67], v[66:67], v[74:75] op_sel_hi:[1,0]
	v_mul_f32_e32 v76, 0xbfb8aa3b, v61
	v_pk_mul_f32 v[62:63], v[62:63], v[74:75] op_sel_hi:[1,0]
	v_pk_mul_f32 v[56:57], v[56:57], v[74:75] op_sel_hi:[1,0]
	v_pk_mul_f32 v[72:73], v[72:73], v[74:75] op_sel_hi:[1,0]
	v_pk_mul_f32 v[58:59], v[58:59], v[74:75] op_sel_hi:[1,0]
	v_mul_f32_e32 v74, 0xbfb8aa3b, v71
	v_mul_f32_e32 v75, 0xbfb8aa3b, v65
	v_mul_f32_e32 v77, 0xbfb8aa3b, v67
	v_exp_f32_e32 v76, v76
	v_exp_f32_e32 v74, v74
	v_exp_f32_e32 v75, v75
	v_exp_f32_e32 v77, v77
	v_add_f32_e32 v76, 1.0, v76
	v_mul_f32_e32 v79, 0xbfb8aa3b, v57
	v_add_f32_e32 v74, 1.0, v74
	v_add_f32_e32 v75, 1.0, v75
	v_add_f32_e32 v77, 1.0, v77
	v_rcp_f32_e32 v76, v76
	v_mul_f32_e32 v80, 0xbfb8aa3b, v73
	v_exp_f32_e32 v79, v79
	v_rcp_f32_e32 v74, v74
	v_rcp_f32_e32 v75, v75
	v_rcp_f32_e32 v77, v77
	v_mul_f32_e32 v78, 0xbfb8aa3b, v63
	v_mul_f32_e32 v81, 0xbfb8aa3b, v59
	v_exp_f32_e32 v80, v80
	v_exp_f32_e32 v78, v78
	v_exp_f32_e32 v81, v81
	v_mul_f32_e32 v61, v61, v76
	v_add_f32_e32 v79, 1.0, v79
	v_mul_f32_e32 v71, v71, v74
	v_mul_f32_e32 v65, v65, v75
	v_mul_f32_e32 v67, v67, v77
	v_mul_f32_e32 v61, v60, v61
	v_add_f32_e32 v80, 1.0, v80
	v_rcp_f32_e32 v79, v79
	v_mul_f32_e32 v70, v70, v71
	v_mul_f32_e32 v64, v64, v65
	v_mul_f32_e32 v65, v66, v67
	v_cvt_pk_bf16_f32 v60, v70, v64
	v_cvt_pk_bf16_f32 v61, v61, v65
	v_add_f32_e32 v78, 1.0, v78
	global_store_dwordx2 v[68:69], v[60:61], off
	v_rcp_f32_e32 v60, v80
	v_add_f32_e32 v61, 1.0, v81
	v_rcp_f32_e32 v78, v78
	v_rcp_f32_e32 v61, v61
	v_mul_f32_e32 v57, v57, v79
	v_mul_f32_e32 v56, v56, v57
	v_mul_f32_e32 v57, v73, v60
	v_mul_f32_e32 v63, v63, v78
	v_mul_f32_e32 v57, v72, v57
	v_mul_f32_e32 v59, v59, v61
	v_mul_f32_e32 v62, v62, v63
	v_mul_f32_e32 v58, v58, v59
	v_cvt_pk_bf16_f32 v56, v62, v56
	v_cvt_pk_bf16_f32 v57, v57, v58
	global_store_dwordx2 v[68:69], v[56:57], off offset:32
	global_load_dword v58, v[54:55], off offset:64
	v_mov_b32_e32 v57, v40
	v_mov_b32_e32 v40, v49
	v_mov_b32_e32 v49, v42
	v_mov_b32_e32 v42, v51
	v_mov_b32_e32 v51, v36
	v_mov_b32_e32 v36, v45
	v_mov_b32_e32 v45, v38
	v_mov_b32_e32 v38, v47
	v_mov_b32_e32 v56, v48
	v_mov_b32_e32 v48, v50
	v_mov_b32_e32 v50, v44
	v_mov_b32_e32 v44, v46
	v_add_u32_e32 v46, 16, v2
	s_waitcnt vmcnt(0)
	v_fmamk_f32 v47, v58, 0x3a800000, v200
	v_mul_f32_e32 v58, 0x4b800000, v47
	v_cmp_gt_f32_e32 vcc, s83, v47
	s_nop 1
	v_cndmask_b32_e32 v47, v47, v58, vcc
	v_rsq_f32_e32 v58, v47
	v_mad_i64_i32 v[46:47], s[24:25], v46, s33, v[0:1]
	v_lshl_add_u64 v[46:47], v[46:47], 0, v[52:53]
	v_mul_f32_e32 v59, 0x45800000, v58
	v_cndmask_b32_e32 v58, v58, v59, vcc
	v_pk_mul_f32 v[56:57], v[56:57], v[58:59] op_sel_hi:[1,0]
	v_pk_mul_f32 v[40:41], v[40:41], v[58:59] op_sel_hi:[1,0]
	v_pk_mul_f32 v[48:49], v[48:49], v[58:59] op_sel_hi:[1,0]
	v_pk_mul_f32 v[42:43], v[42:43], v[58:59] op_sel_hi:[1,0]
	v_pk_mul_f32 v[36:37], v[36:37], v[58:59] op_sel_hi:[1,0]
	v_pk_mul_f32 v[38:39], v[38:39], v[58:59] op_sel_hi:[1,0]
	v_pk_mul_f32 v[50:51], v[50:51], v[58:59] op_sel_hi:[1,0]
	v_pk_mul_f32 v[44:45], v[44:45], v[58:59] op_sel_hi:[1,0]
	v_mul_f32_e32 v58, 0xbfb8aa3b, v57
	v_mul_f32_e32 v59, 0xbfb8aa3b, v41
	v_mul_f32_e32 v60, 0xbfb8aa3b, v49
	v_mul_f32_e32 v61, 0xbfb8aa3b, v43
	v_mul_f32_e32 v63, 0xbfb8aa3b, v37
	v_mul_f32_e32 v65, 0xbfb8aa3b, v39
	v_mul_f32_e32 v62, 0xbfb8aa3b, v51
	v_mul_f32_e32 v64, 0xbfb8aa3b, v45
	v_exp_f32_e32 v58, v58
	v_exp_f32_e32 v59, v59
	v_exp_f32_e32 v60, v60
	v_exp_f32_e32 v61, v61
	v_exp_f32_e32 v63, v63
	v_exp_f32_e32 v65, v65
	v_exp_f32_e32 v62, v62
	v_exp_f32_e32 v64, v64
	v_add_f32_e32 v58, 1.0, v58
	v_add_f32_e32 v59, 1.0, v59
	v_add_f32_e32 v60, 1.0, v60
	v_add_f32_e32 v61, 1.0, v61
	v_add_f32_e32 v63, 1.0, v63
	v_add_f32_e32 v65, 1.0, v65
	v_add_f32_e32 v62, 1.0, v62
	v_add_f32_e32 v64, 1.0, v64
	v_rcp_f32_e32 v58, v58
	v_rcp_f32_e32 v59, v59
	v_rcp_f32_e32 v60, v60
	v_rcp_f32_e32 v61, v61
	v_rcp_f32_e32 v63, v63
	v_rcp_f32_e32 v65, v65
	v_rcp_f32_e32 v62, v62
	v_rcp_f32_e32 v64, v64
	v_mul_f32_e32 v57, v57, v58
	v_mul_f32_e32 v41, v41, v59
	v_mul_f32_e32 v49, v49, v60
	v_mul_f32_e32 v43, v43, v61
	v_mul_f32_e32 v37, v37, v63
	v_mul_f32_e32 v39, v39, v65
	v_mul_f32_e32 v51, v51, v62
	v_mul_f32_e32 v45, v45, v64
	v_mul_f32_e32 v56, v56, v57
	v_mul_f32_e32 v40, v40, v41
	v_mul_f32_e32 v41, v48, v49
	v_mul_f32_e32 v42, v42, v43
	v_mul_f32_e32 v48, v36, v37
	v_mul_f32_e32 v39, v38, v39
	v_cvt_pk_bf16_f32 v36, v56, v40
	v_cvt_pk_bf16_f32 v37, v41, v42
	v_mul_f32_e32 v43, v50, v51
	v_mul_f32_e32 v44, v44, v45
	v_cvt_pk_bf16_f32 v38, v43, v48
	v_cvt_pk_bf16_f32 v39, v44, v39
	global_store_dwordx2 v[46:47], v[36:37], off
	global_store_dwordx2 v[46:47], v[38:39], off offset:32
	global_load_dword v38, v[54:55], off offset:128
	v_mov_b32_e32 v37, v24
	v_mov_b32_e32 v24, v33
	v_mov_b32_e32 v33, v26
	v_mov_b32_e32 v26, v35
	v_mov_b32_e32 v35, v20
	v_mov_b32_e32 v20, v29
	v_mov_b32_e32 v29, v22
	v_mov_b32_e32 v22, v31
	v_mov_b32_e32 v36, v32
	v_mov_b32_e32 v32, v34
	v_mov_b32_e32 v34, v28
	v_mov_b32_e32 v28, v30
	v_add_u32_e32 v30, 32, v2
	v_add_u32_e32 v2, 48, v2
	s_waitcnt vmcnt(0)
; __device__ __forceinline__ unsigned pk2(float lo, float hi) { unsigned r; asm("v_cvt_pk_bf16_f32 %0, %1, %2" : "=v"(r) : "v"(lo), "v"(hi)); return r; }
; __device__ __forceinline__ float sigmoidf_(float x) { return __builtin_amdgcn_rcpf(1.0f + __expf(-x)); }
; __device__ __forceinline__ void gemm_GU(const Params& p, int item, char* lds) {
;     ...
;   for (int m = 0; m < 4; m++) {
;     const int rl = wr * 64 + m * 16 + fr; const float r = rsqrtf(rssg[rl] * (1.f / 1024.f) + 1e-6f);
; #pragma unroll
;     for (int i = 0; i < 2; i++) {
;       f32x4 g = acc[m][2 * i] * r, u = acc[m][2 * i + 1] * r, o;
; #pragma unroll
;       for (int j = 0; j < 4; j++) o[j] = g[j] * sigmoidf_(g[j]) * u[j];
;       const int col = (n0 >> 1) + wc * 32 + i * 16 + fq * 4;
;       u32x2 w; w[0] = pk2(o[0], o[1]); w[1] = pk2(o[2], o[3]);
;       *(u32x2*)(U + (size_t)(m0 + rl) * DFF + col) = w;
;     }
;   }
;   __syncthreads();
; }
	v_fmamk_f32 v31, v38, 0x3a800000, v200
	v_mul_f32_e32 v38, 0x4b800000, v31
	v_cmp_gt_f32_e32 vcc, s83, v31
	s_nop 1
	v_cndmask_b32_e32 v31, v31, v38, vcc
	v_rsq_f32_e32 v38, v31
	v_mad_i64_i32 v[30:31], s[24:25], v30, s33, v[0:1]
	v_lshl_add_u64 v[30:31], v[30:31], 0, v[52:53]
	v_mul_f32_e32 v39, 0x45800000, v38
	v_cndmask_b32_e32 v38, v38, v39, vcc
	v_pk_mul_f32 v[36:37], v[36:37], v[38:39] op_sel_hi:[1,0]
	v_pk_mul_f32 v[24:25], v[24:25], v[38:39] op_sel_hi:[1,0]
	v_pk_mul_f32 v[32:33], v[32:33], v[38:39] op_sel_hi:[1,0]
	v_pk_mul_f32 v[26:27], v[26:27], v[38:39] op_sel_hi:[1,0]
	v_pk_mul_f32 v[20:21], v[20:21], v[38:39] op_sel_hi:[1,0]
	v_pk_mul_f32 v[22:23], v[22:23], v[38:39] op_sel_hi:[1,0]
	v_pk_mul_f32 v[34:35], v[34:35], v[38:39] op_sel_hi:[1,0]
	v_pk_mul_f32 v[28:29], v[28:29], v[38:39] op_sel_hi:[1,0]
	v_mul_f32_e32 v38, 0xbfb8aa3b, v37
	v_mul_f32_e32 v39, 0xbfb8aa3b, v25
	v_mul_f32_e32 v40, 0xbfb8aa3b, v33
	v_mul_f32_e32 v41, 0xbfb8aa3b, v27
	v_mul_f32_e32 v43, 0xbfb8aa3b, v21
	v_mul_f32_e32 v45, 0xbfb8aa3b, v23
	v_mul_f32_e32 v42, 0xbfb8aa3b, v35
	v_mul_f32_e32 v44, 0xbfb8aa3b, v29
	v_exp_f32_e32 v38, v38
	v_exp_f32_e32 v39, v39
	v_exp_f32_e32 v40, v40
	v_exp_f32_e32 v41, v41
	v_exp_f32_e32 v43, v43
	v_exp_f32_e32 v45, v45
	v_exp_f32_e32 v42, v42
	v_exp_f32_e32 v44, v44
	v_add_f32_e32 v38, 1.0, v38
	v_add_f32_e32 v39, 1.0, v39
	v_add_f32_e32 v40, 1.0, v40
	v_add_f32_e32 v41, 1.0, v41
	v_add_f32_e32 v43, 1.0, v43
	v_add_f32_e32 v45, 1.0, v45
	v_add_f32_e32 v42, 1.0, v42
	v_add_f32_e32 v44, 1.0, v44
	v_rcp_f32_e32 v38, v38
	v_rcp_f32_e32 v39, v39
	v_rcp_f32_e32 v40, v40
	v_rcp_f32_e32 v41, v41
	v_rcp_f32_e32 v43, v43
	v_rcp_f32_e32 v45, v45
	v_rcp_f32_e32 v42, v42
	v_rcp_f32_e32 v44, v44
	v_mul_f32_e32 v37, v37, v38
	v_mul_f32_e32 v25, v25, v39
	v_mul_f32_e32 v33, v33, v40
	v_mul_f32_e32 v27, v27, v41
	v_mul_f32_e32 v21, v21, v43
	v_mul_f32_e32 v23, v23, v45
	v_mul_f32_e32 v35, v35, v42
	v_mul_f32_e32 v29, v29, v44
	v_mul_f32_e32 v36, v36, v37
	v_mul_f32_e32 v24, v24, v25
	v_mul_f32_e32 v25, v32, v33
	v_mul_f32_e32 v26, v26, v27
	v_mul_f32_e32 v32, v20, v21
	v_mul_f32_e32 v23, v22, v23
	v_cvt_pk_bf16_f32 v20, v36, v24
	v_cvt_pk_bf16_f32 v21, v25, v26
	v_mul_f32_e32 v27, v34, v35
	v_mul_f32_e32 v28, v28, v29
	v_cvt_pk_bf16_f32 v22, v27, v32
	v_cvt_pk_bf16_f32 v23, v28, v23
	global_store_dwordx2 v[30:31], v[20:21], off
	global_store_dwordx2 v[30:31], v[22:23], off offset:32
	global_load_dword v22, v[54:55], off offset:192
	v_mov_b32_e32 v20, v16
	v_mov_b32_e32 v16, v18
	v_mov_b32_e32 v18, v12
	v_mov_b32_e32 v12, v14
	v_mov_b32_e32 v21, v8
	v_mov_b32_e32 v8, v17
	v_mov_b32_e32 v17, v10
	v_mov_b32_e32 v10, v19
	v_mov_b32_e32 v19, v4
	v_mov_b32_e32 v4, v13
	v_mov_b32_e32 v13, v6
	v_mov_b32_e32 v6, v15
	v_mad_i64_i32 v[0:1], s[24:25], v2, s33, v[0:1]
	v_lshl_add_u64 v[0:1], v[0:1], 0, v[52:53]
	s_waitcnt vmcnt(0)
	v_fmamk_f32 v14, v22, 0x3a800000, v200
	v_mul_f32_e32 v15, 0x4b800000, v14
	v_cmp_gt_f32_e32 vcc, s83, v14
	s_nop 1
	v_cndmask_b32_e32 v14, v14, v15, vcc
	v_rsq_f32_e32 v14, v14
	s_nop 0
	v_mul_f32_e32 v2, 0x45800000, v14
	v_cndmask_b32_e32 v2, v14, v2, vcc
	v_pk_mul_f32 v[14:15], v[20:21], v[2:3] op_sel_hi:[1,0]
	v_pk_mul_f32 v[8:9], v[8:9], v[2:3] op_sel_hi:[1,0]
	v_pk_mul_f32 v[16:17], v[16:17], v[2:3] op_sel_hi:[1,0]
	v_pk_mul_f32 v[10:11], v[10:11], v[2:3] op_sel_hi:[1,0]
	v_pk_mul_f32 v[4:5], v[4:5], v[2:3] op_sel_hi:[1,0]
	v_pk_mul_f32 v[6:7], v[6:7], v[2:3] op_sel_hi:[1,0]
	v_pk_mul_f32 v[18:19], v[18:19], v[2:3] op_sel_hi:[1,0]
	v_pk_mul_f32 v[12:13], v[12:13], v[2:3] op_sel_hi:[1,0]
	v_mul_f32_e32 v2, 0xbfb8aa3b, v15
	v_mul_f32_e32 v20, 0xbfb8aa3b, v9
	v_mul_f32_e32 v21, 0xbfb8aa3b, v17
	v_mul_f32_e32 v22, 0xbfb8aa3b, v11
	v_mul_f32_e32 v24, 0xbfb8aa3b, v5
	v_mul_f32_e32 v26, 0xbfb8aa3b, v7
	v_mul_f32_e32 v23, 0xbfb8aa3b, v19
	v_mul_f32_e32 v25, 0xbfb8aa3b, v13
	v_exp_f32_e32 v2, v2
	v_exp_f32_e32 v20, v20
	v_exp_f32_e32 v21, v21
	v_exp_f32_e32 v22, v22
	v_exp_f32_e32 v24, v24
	v_exp_f32_e32 v26, v26
	v_exp_f32_e32 v23, v23
	v_exp_f32_e32 v25, v25
	v_add_f32_e32 v2, 1.0, v2
	v_add_f32_e32 v20, 1.0, v20
	v_add_f32_e32 v21, 1.0, v21
	v_add_f32_e32 v22, 1.0, v22
	v_add_f32_e32 v24, 1.0, v24
	v_add_f32_e32 v26, 1.0, v26
	v_add_f32_e32 v23, 1.0, v23
	v_add_f32_e32 v25, 1.0, v25
	v_rcp_f32_e32 v2, v2
	v_rcp_f32_e32 v20, v20
	v_rcp_f32_e32 v21, v21
	v_rcp_f32_e32 v22, v22
	v_rcp_f32_e32 v24, v24
	v_rcp_f32_e32 v26, v26
	v_rcp_f32_e32 v23, v23
	v_rcp_f32_e32 v25, v25
	v_mul_f32_e32 v2, v15, v2
	v_mul_f32_e32 v9, v9, v20
	v_mul_f32_e32 v15, v17, v21
	v_mul_f32_e32 v11, v11, v22
	v_mul_f32_e32 v5, v5, v24
	v_mul_f32_e32 v7, v7, v26
	v_mul_f32_e32 v17, v19, v23
	v_mul_f32_e32 v13, v13, v25
	v_mul_f32_e32 v2, v14, v2
	v_mul_f32_e32 v8, v8, v9
	v_mul_f32_e32 v9, v16, v15
	v_mul_f32_e32 v10, v10, v11
	v_mul_f32_e32 v14, v4, v5
	v_mul_f32_e32 v7, v6, v7
	v_cvt_pk_bf16_f32 v4, v2, v8
	v_cvt_pk_bf16_f32 v5, v9, v10
	v_mul_f32_e32 v11, v18, v17
	v_mul_f32_e32 v12, v12, v13
	v_cvt_pk_bf16_f32 v6, v11, v14
	v_cvt_pk_bf16_f32 v7, v12, v7
	global_store_dwordx2 v[0:1], v[4:5], off
	global_store_dwordx2 v[0:1], v[6:7], off offset:32
	s_barrier
	s_cbranch_scc0 .LBB0_108

; __device__ __forceinline__ int opaque_tid() { int t = threadIdx.x; asm volatile("" : "+v"(t)); return t; }
; __device__ __forceinline__ void gemm_mainloop_d(const bf16_t* __restrict__ Ap, int lda, const bf16_t* __restrict__ Bt, int K,
;                                                 int m0, int n0, f32x4 (&acc)[4][4], char* lds) {
;   const int tid = opaque_tid(), lane = tid & 63, wid = tid >> 6, wr = wid >> 1, wc = wid & 1, fr = lane & 15, fq = lane >> 4;
; #pragma unroll
;   for (int m = 0; m < 4; m++)
; #pragma unroll
;     for (int n = 0; n < 4; n++) acc[m][n] = (f32x4){0.f, 0.f, 0.f, 0.f};
;   const int nk = K >> 6;
;   const int lrow = tid >> 3, cph = tid & 7;
;   auto dma = [&](int kt, int st) {
;     char* la = lds + st * 32768; char* lb = la + 16384;
; #pragma unroll
;     for (int i = 0; i < 4; i++) {
;       const int row = i * 32 + lrow; const int c = cph ^ ((row >> 1) & 7);
;       __builtin_amdgcn_global_load_lds((const unsigned*)(Ap + (size_t)(m0 + row) * lda + kt * 64 + c * 8), (__attribute__((address_space(3))) unsigned*)(la + i * 4096 + tid * 16), 16, 0, 0);
;       __builtin_amdgcn_global_load_lds((const unsigned*)(Bt + (size_t)(n0 + row) * K + kt * 64 + c * 8), (__attribute__((address_space(3))) unsigned*)(lb + i * 4096 + tid * 16), 16, 0, 0);
;     }
;   };
;   dma(0, 0);
;   asm volatile("s_waitcnt vmcnt(0)" ::: "memory"); __builtin_amdgcn_s_barrier(); asm volatile("" ::: "memory");
; __device__ __forceinline__ void gemm_RES(const bf16_t* A, int K, const bf16_t* Bt, const float* xin, float* xout, bf16_t* xb, float* rss, int item, char* lds) {
;   const int mt = item >> 3, nt = item & 7; const int m0 = mt * 128, n0 = nt * 128;
;   f32x4 acc[4][4];
;   gemm_mainloop_d(A, K, Bt, K, m0, n0, acc, lds);
.LBB0_125:
	s_and_b32 s43, s41, 0xffffff80
	s_and_b32 s37, s40, 0x380
	s_mov_b32 s44, 0
	s_add_u32 s2, s46, s44
	s_addc_u32 s3, s47, 0
	s_add_u32 s30, s2, 0xc0a8000
	s_addc_u32 s31, s3, 0
	s_mov_b32 s35, 0
	s_mov_b32 s36, 0
	s_lshl_b32 s2, s42, 4
	v_mov_b32_e32 v4, v198
	s_and_b32 s3, s2, 0xffffff80
	s_lshl_b32 s2, s42, 7
	v_ashrrev_i32_e32 v7, 3, v4
	v_lshrrev_b32_e32 v8, 1, v7
	v_add_u32_e32 v0, s3, v7
	v_xor_b32_e32 v2, v8, v4
	v_ashrrev_i32_e32 v1, 31, v0
	v_lshlrev_b64 v[0:1], 11, v[0:1]
	v_lshlrev_b32_e32 v2, 4, v2
	v_lshl_add_u32 v82, v4, 4, 0
	v_lshl_add_u64 v[0:1], s[30:31], 0, v[0:1]
	v_and_b32_e32 v2, 0x70, v2
	v_readfirstlane_b32 s45, v82
	s_and_b32 s2, s2, 0x380
	v_lshl_add_u64 v[0:1], v[0:1], 0, v[2:3]
	s_mov_b32 m0, s45
	v_add_u32_e32 v9, 0x4000, v82
	global_load_lds_dwordx4 v[0:1], off
	v_add_u32_e32 v0, s2, v7
	v_ashrrev_i32_e32 v1, 31, v0
	v_lshlrev_b64 v[0:1], 11, v[0:1]
	v_lshl_add_u64 v[0:1], s[24:25], 0, v[0:1]
	v_readfirstlane_b32 s45, v9
	v_lshl_add_u64 v[0:1], v[0:1], 0, v[2:3]
	s_mov_b32 m0, s45
	v_add_u32_e32 v9, 32, v7
	global_load_lds_dwordx4 v[0:1], off
	v_add_u32_e32 v0, s3, v9
	v_ashrrev_i32_e32 v1, 31, v0
	v_lshlrev_b64 v[0:1], 11, v[0:1]
	v_add_u32_e32 v10, 0x1000, v82
	v_lshl_add_u64 v[0:1], s[30:31], 0, v[0:1]
	v_readfirstlane_b32 s45, v10
	v_lshl_add_u64 v[0:1], v[0:1], 0, v[2:3]
	s_mov_b32 m0, s45
	v_add_u32_e32 v10, 0x5000, v82
	global_load_lds_dwordx4 v[0:1], off
	v_add_u32_e32 v0, s2, v9
	v_ashrrev_i32_e32 v1, 31, v0
	v_lshlrev_b64 v[0:1], 11, v[0:1]
	v_lshl_add_u64 v[0:1], s[24:25], 0, v[0:1]
	v_readfirstlane_b32 s45, v10
	v_lshl_add_u64 v[0:1], v[0:1], 0, v[2:3]
	s_mov_b32 m0, s45
	v_add_u32_e32 v10, 64, v7
	global_load_lds_dwordx4 v[0:1], off
	v_add_u32_e32 v0, s3, v10
	v_ashrrev_i32_e32 v1, 31, v0
	v_lshlrev_b64 v[0:1], 11, v[0:1]
	v_add_u32_e32 v11, 0x2000, v82
	v_lshl_add_u64 v[0:1], s[30:31], 0, v[0:1]
	v_readfirstlane_b32 s45, v11
	v_lshl_add_u64 v[0:1], v[0:1], 0, v[2:3]
	s_mov_b32 m0, s45
	v_add_u32_e32 v11, 0x6000, v82
	global_load_lds_dwordx4 v[0:1], off
	v_add_u32_e32 v0, s2, v10
	v_ashrrev_i32_e32 v1, 31, v0
	v_lshlrev_b64 v[0:1], 11, v[0:1]
	v_lshl_add_u64 v[0:1], s[24:25], 0, v[0:1]
	v_readfirstlane_b32 s45, v11
	v_lshl_add_u64 v[0:1], v[0:1], 0, v[2:3]
	s_mov_b32 m0, s45
	v_add_u32_e32 v11, 0x60, v7
	global_load_lds_dwordx4 v[0:1], off
	v_add_u32_e32 v0, s3, v11
	v_ashrrev_i32_e32 v1, 31, v0
	v_lshlrev_b64 v[0:1], 11, v[0:1]
	v_add_u32_e32 v12, 0x3000, v82
	v_lshl_add_u64 v[0:1], s[30:31], 0, v[0:1]
	v_readfirstlane_b32 s30, v12
	v_lshl_add_u64 v[0:1], v[0:1], 0, v[2:3]
	s_mov_b32 m0, s30
	s_mov_b32 s4, 0x1ffffc0
	global_load_lds_dwordx4 v[0:1], off
	v_add_u32_e32 v0, s2, v11
	v_ashrrev_i32_e32 v1, 31, v0
	v_lshlrev_b64 v[0:1], 11, v[0:1]
	v_lshl_add_u64 v[0:1], s[24:25], 0, v[0:1]
	v_lshl_add_u64 v[0:1], v[0:1], 0, v[2:3]
	v_add_u32_e32 v2, 0x7000, v82
	v_lshrrev_b32_e32 v5, 4, v4
	v_readfirstlane_b32 s30, v2
	s_mov_b32 m0, s30
	v_bfe_u32 v6, v4, 4, 2
	global_load_lds_dwordx4 v[0:1], off
	v_and_b32_e32 v0, 15, v4
	v_lshrrev_b32_e32 v1, 1, v4
	v_and_or_b32 v0, v1, s4, v0
	v_bfe_u32 v1, v4, 1, 3
	v_lshlrev_b32_e32 v2, 7, v4
	v_bitop3_b32 v5, v5, v1, 3 bitop3:0x6c
	v_bitop3_b32 v4, v8, 7, v4 bitop3:0x48
	v_and_b32_e32 v2, 0x2780, v2
	v_lshlrev_b32_e32 v5, 4, v5
	v_lshlrev_b32_e32 v0, 7, v0
	v_bitop3_b32 v1, v6, v1, 4 bitop3:0x36
	v_lshlrev_b32_e32 v6, 4, v4
	v_add_u32_e32 v4, s37, v7
	v_or_b32_e32 v85, v0, v5
	v_or_b32_e32 v84, v5, v2
	v_ashrrev_i32_e32 v5, 31, v4
	v_lshlrev_b64 v[4:5], 11, v[4:5]
	v_or_b32_e32 v4, v4, v6
	s_waitcnt vmcnt(0)
	v_lshl_add_u64 v[68:69], s[28:29], 0, v[4:5]
	v_add_u32_e32 v4, s43, v9
	v_readlane_b32 s4, v254, 49
	v_ashrrev_i32_e32 v5, 31, v4
	s_add_u32 s30, s4, s44
	v_readlane_b32 s4, v254, 50
	v_lshlrev_b64 v[4:5], 11, v[4:5]
	s_addc_u32 s31, s4, 0
	v_or_b32_e32 v4, v4, v6
	v_lshl_add_u64 v[70:71], s[30:31], 0, v[4:5]
	v_add_u32_e32 v4, s37, v9
	v_ashrrev_i32_e32 v5, 31, v4
	v_lshlrev_b64 v[4:5], 11, v[4:5]
	v_or_b32_e32 v4, v4, v6
	v_lshl_add_u64 v[72:73], s[28:29], 0, v[4:5]
	v_add_u32_e32 v4, s43, v10
	v_ashrrev_i32_e32 v5, 31, v4
	v_lshlrev_b64 v[4:5], 11, v[4:5]
	v_or_b32_e32 v4, v4, v6
	v_lshl_add_u64 v[74:75], s[30:31], 0, v[4:5]
	v_add_u32_e32 v4, s37, v10
	v_ashrrev_i32_e32 v5, 31, v4
	v_lshlrev_b64 v[4:5], 11, v[4:5]
	v_or_b32_e32 v4, v4, v6
	v_lshl_add_u64 v[76:77], s[28:29], 0, v[4:5]
	v_add_u32_e32 v4, s43, v11
	v_ashrrev_i32_e32 v5, 31, v4
	v_lshlrev_b64 v[4:5], 11, v[4:5]
	v_or_b32_e32 v4, v4, v6
	v_lshlrev_b32_e32 v1, 4, v1
	v_lshl_add_u64 v[78:79], s[30:31], 0, v[4:5]
	v_add_u32_e32 v4, s37, v11
	v_or_b32_e32 v83, v1, v0
	v_add_u32_e32 v0, s43, v7
	v_ashrrev_i32_e32 v5, 31, v4
	v_or_b32_e32 v2, v1, v2
	v_ashrrev_i32_e32 v1, 31, v0
	v_lshlrev_b64 v[4:5], 11, v[4:5]
	s_waitcnt vmcnt(0)
	s_barrier
	v_lshlrev_b64 v[0:1], 11, v[0:1]
	v_or_b32_e32 v4, v4, v6
	v_or_b32_e32 v0, v0, v6
	v_lshl_add_u64 v[80:81], s[28:29], 0, v[4:5]
	v_mov_b32_e32 v4, 0
	s_mov_b32 s34, 0
	v_lshl_add_u64 v[0:1], s[30:31], 0, v[0:1]
	s_mov_b64 s[30:31], 0
	v_mov_b32_e32 v5, v4
	v_mov_b32_e32 v6, v4
	v_mov_b32_e32 v7, v4
	v_mov_b32_e32 v8, v4
	v_mov_b32_e32 v9, v4
	v_mov_b32_e32 v10, v4
	v_mov_b32_e32 v11, v4
	v_mov_b32_e32 v12, v4
	v_mov_b32_e32 v13, v4
	v_mov_b32_e32 v14, v4
	v_mov_b32_e32 v15, v4
	v_mov_b32_e32 v16, v4
	v_mov_b32_e32 v17, v4
	v_mov_b32_e32 v18, v4
	v_mov_b32_e32 v19, v4
	v_mov_b32_e32 v20, v4
	v_mov_b32_e32 v21, v4
	v_mov_b32_e32 v22, v4
	v_mov_b32_e32 v23, v4
	v_mov_b32_e32 v24, v4
	v_mov_b32_e32 v25, v4
	v_mov_b32_e32 v26, v4
	v_mov_b32_e32 v27, v4
	v_mov_b32_e32 v28, v4
	v_mov_b32_e32 v29, v4
	v_mov_b32_e32 v30, v4
	v_mov_b32_e32 v31, v4
	v_mov_b32_e32 v32, v4
	v_mov_b32_e32 v33, v4
	v_mov_b32_e32 v34, v4
	v_mov_b32_e32 v35, v4
	v_mov_b32_e32 v36, v4
	v_mov_b32_e32 v37, v4
	v_mov_b32_e32 v38, v4
	v_mov_b32_e32 v39, v4
	v_mov_b32_e32 v40, v4
	v_mov_b32_e32 v41, v4
	v_mov_b32_e32 v42, v4
	v_mov_b32_e32 v43, v4
	v_mov_b32_e32 v44, v4
	v_mov_b32_e32 v45, v4
	v_mov_b32_e32 v46, v4
	v_mov_b32_e32 v47, v4
	v_mov_b32_e32 v48, v4
	v_mov_b32_e32 v49, v4
	v_mov_b32_e32 v50, v4
	v_mov_b32_e32 v51, v4
	v_mov_b32_e32 v52, v4
	v_mov_b32_e32 v53, v4
	v_mov_b32_e32 v54, v4
	v_mov_b32_e32 v55, v4
	v_mov_b32_e32 v56, v4
	v_mov_b32_e32 v57, v4
	v_mov_b32_e32 v58, v4
	v_mov_b32_e32 v59, v4
	v_mov_b32_e32 v60, v4
	v_mov_b32_e32 v61, v4
	v_mov_b32_e32 v62, v4
	v_mov_b32_e32 v63, v4
	v_mov_b32_e32 v64, v4
	v_mov_b32_e32 v65, v4
	v_mov_b32_e32 v66, v4
	v_mov_b32_e32 v67, v4
	v_subrev_u32_e32 v150, s46, v0
	v_subrev_u32_e32 v151, s46, v68
	v_subrev_u32_e32 v152, s46, v70
	v_subrev_u32_e32 v153, s46, v72
	v_subrev_u32_e32 v154, s46, v74
	v_subrev_u32_e32 v155, s46, v76
	v_subrev_u32_e32 v156, s46, v78
	v_subrev_u32_e32 v157, s46, v80
	v_readfirstlane_b32 vcc_hi, v82
; __device__ __forceinline__ void gemm_mainloop_d(const bf16_t* __restrict__ Ap, int lda, const bf16_t* __restrict__ Bt, int K,
;                                                 int m0, int n0, f32x4 (&acc)[4][4], char* lds) {
;     ...
;   for (int kt = 0; kt < nk; kt++) {
;     const int st = kt & 1;
;     if (kt + 1 < nk) dma(kt + 1, st ^ 1);
;     const char* la = lds + st * 32768; const char* lb = la + 16384;
;     bf16x8 af[2][4], bfv[2][4];
; #pragma unroll
;     for (int kc = 0; kc < 2; kc++) {
; #pragma unroll
;       for (int m = 0; m < 4; m++) { const int row = wr * 64 + m * 16 + fr; af[kc][m] = *(const bf16x8*)(la + (row * 8 + ((kc * 4 + fq) ^ ((row >> 1) & 7))) * 16); }
; #pragma unroll
;       for (int n = 0; n < 4; n++) { const int row = wc * 64 + n * 16 + fr; bfv[kc][n] = *(const bf16x8*)(lb + (row * 8 + ((kc * 4 + fq) ^ ((row >> 1) & 7))) * 16); }
;     }
;     __builtin_amdgcn_s_setprio(1);
; #pragma unroll
;     for (int kc = 0; kc < 2; kc++)
; #pragma unroll
;       for (int m = 0; m < 4; m++)
; #pragma unroll
;         for (int n = 0; n < 4; n++) acc[m][n] = __builtin_amdgcn_mfma_f32_16x16x32_bf16(bfv[kc][n], af[kc][m], acc[m][n], 0, 0, 0);
;     __builtin_amdgcn_s_setprio(0);
;     asm volatile("s_waitcnt vmcnt(0) lgkmcnt(0)" ::: "memory"); __builtin_amdgcn_s_barrier(); asm volatile("" ::: "memory");
;   }
.LBB0_126:
	s_and_b32 s37, s34, 0x8000
	s_xor_b32 s43, s37, 0x8000
	s_add_i32 s43, s43, vcc_hi
	s_mov_b32 m0, s43
	s_add_i32 vcc_lo, s43, 0x4000
	global_load_lds_dwordx4 v150, s[46:47]
	s_mov_b32 m0, vcc_lo
	s_add_i32 vcc_lo, s43, 0x1000
	global_load_lds_dwordx4 v151, s[46:47]
	s_mov_b32 m0, vcc_lo
	s_add_i32 vcc_lo, s43, 0x5000
	global_load_lds_dwordx4 v152, s[46:47]
	s_mov_b32 m0, vcc_lo
	s_add_i32 vcc_lo, s43, 0x2000
	global_load_lds_dwordx4 v153, s[46:47]
	s_mov_b32 m0, vcc_lo
	s_add_i32 vcc_lo, s43, 0x6000
	global_load_lds_dwordx4 v154, s[46:47]
	s_mov_b32 m0, vcc_lo
	s_add_i32 vcc_lo, s43, 0x3000
	global_load_lds_dwordx4 v155, s[46:47]
	s_mov_b32 m0, vcc_lo
	s_add_i32 vcc_lo, s43, 0x7000
	global_load_lds_dwordx4 v156, s[46:47]
	s_mov_b32 m0, vcc_lo
	s_nop 0
	global_load_lds_dwordx4 v157, s[46:47]
	v_add_u32_e32 v150, 0x80, v150
	v_add_u32_e32 v151, 0x80, v151
	v_add_u32_e32 v152, 0x80, v152
	v_add_u32_e32 v153, 0x80, v153
	v_add_u32_e32 v154, 0x80, v154
	v_add_u32_e32 v155, 0x80, v155
	v_add_u32_e32 v156, 0x80, v156
	v_add_u32_e32 v157, 0x80, v157
	v_add_u32_e32 v98, s37, v85
	v_add_u32_e32 v114, s37, v84
	v_add_u32_e32 v130, s37, v83
	v_add_u32_e32 v146, s37, v2
	ds_read_b128 v[86:89], v98
	ds_read_b128 v[90:93], v98 offset:2048
	ds_read_b128 v[94:97], v98 offset:4096
	ds_read_b128 v[98:101], v98 offset:6144
	ds_read_b128 v[102:105], v114 offset:16384
	ds_read_b128 v[106:109], v114 offset:18432
	ds_read_b128 v[110:113], v114 offset:20480
	ds_read_b128 v[114:117], v114 offset:22528
	ds_read_b128 v[118:121], v130
	ds_read_b128 v[122:125], v130 offset:2048
	ds_read_b128 v[126:129], v130 offset:4096
	ds_read_b128 v[130:133], v130 offset:6144
	ds_read_b128 v[134:137], v146 offset:16384
	ds_read_b128 v[138:141], v146 offset:18432
	ds_read_b128 v[142:145], v146 offset:20480
	ds_read_b128 v[146:149], v146 offset:22528
	s_setprio 1
	s_waitcnt lgkmcnt(0)
	v_mfma_f32_16x16x32_bf16 v[64:67], v[102:105], v[86:89], v[64:67]
	v_mfma_f32_16x16x32_bf16 v[60:63], v[106:109], v[86:89], v[60:63]
	v_mfma_f32_16x16x32_bf16 v[56:59], v[110:113], v[86:89], v[56:59]
	v_mfma_f32_16x16x32_bf16 v[52:55], v[114:117], v[86:89], v[52:55]
	v_mfma_f32_16x16x32_bf16 v[48:51], v[102:105], v[90:93], v[48:51]
	v_mfma_f32_16x16x32_bf16 v[44:47], v[106:109], v[90:93], v[44:47]
	v_mfma_f32_16x16x32_bf16 v[40:43], v[110:113], v[90:93], v[40:43]
	v_mfma_f32_16x16x32_bf16 v[36:39], v[114:117], v[90:93], v[36:39]
	v_mfma_f32_16x16x32_bf16 v[32:35], v[102:105], v[94:97], v[32:35]
	v_mfma_f32_16x16x32_bf16 v[28:31], v[106:109], v[94:97], v[28:31]
	v_mfma_f32_16x16x32_bf16 v[24:27], v[110:113], v[94:97], v[24:27]
	v_mfma_f32_16x16x32_bf16 v[20:23], v[114:117], v[94:97], v[20:23]
	v_mfma_f32_16x16x32_bf16 v[16:19], v[102:105], v[98:101], v[16:19]
	v_mfma_f32_16x16x32_bf16 v[12:15], v[106:109], v[98:101], v[12:15]
	v_mfma_f32_16x16x32_bf16 v[8:11], v[110:113], v[98:101], v[8:11]
	v_mfma_f32_16x16x32_bf16 v[4:7], v[114:117], v[98:101], v[4:7]
	v_mfma_f32_16x16x32_bf16 v[64:67], v[134:137], v[118:121], v[64:67]
	v_mfma_f32_16x16x32_bf16 v[60:63], v[138:141], v[118:121], v[60:63]
	v_mfma_f32_16x16x32_bf16 v[56:59], v[142:145], v[118:121], v[56:59]
	v_mfma_f32_16x16x32_bf16 v[52:55], v[146:149], v[118:121], v[52:55]
	v_mfma_f32_16x16x32_bf16 v[48:51], v[134:137], v[122:125], v[48:51]
	v_mfma_f32_16x16x32_bf16 v[44:47], v[138:141], v[122:125], v[44:47]
	v_mfma_f32_16x16x32_bf16 v[40:43], v[142:145], v[122:125], v[40:43]
	v_mfma_f32_16x16x32_bf16 v[36:39], v[146:149], v[122:125], v[36:39]
	v_mfma_f32_16x16x32_bf16 v[32:35], v[134:137], v[126:129], v[32:35]
	v_mfma_f32_16x16x32_bf16 v[28:31], v[138:141], v[126:129], v[28:31]
	v_mfma_f32_16x16x32_bf16 v[24:27], v[142:145], v[126:129], v[24:27]
	v_mfma_f32_16x16x32_bf16 v[20:23], v[146:149], v[126:129], v[20:23]
	v_mfma_f32_16x16x32_bf16 v[16:19], v[134:137], v[130:133], v[16:19]
	v_mfma_f32_16x16x32_bf16 v[12:15], v[138:141], v[130:133], v[12:15]
	v_mfma_f32_16x16x32_bf16 v[8:11], v[142:145], v[130:133], v[8:11]
	v_mfma_f32_16x16x32_bf16 v[4:7], v[146:149], v[130:133], v[4:7]
	s_setprio 0
	s_waitcnt vmcnt(0) lgkmcnt(0)
	s_barrier
	s_add_u32 s30, s30, 0x80
	s_addc_u32 s31, s31, 0
	s_add_i32 s34, s34, 0x8000
	s_cmpk_eq_i32 s30, 0x780
	s_cbranch_scc0 .LBB0_126
; __device__ __forceinline__ void gemm_mainloop_d(const bf16_t* __restrict__ Ap, int lda, const bf16_t* __restrict__ Bt, int K,
;                                                 int m0, int n0, f32x4 (&acc)[4][4], char* lds) {
;     ...
;   for (int kt = 0; kt < nk; kt++) {
;     const int st = kt & 1;
;     if (kt + 1 < nk) dma(kt + 1, st ^ 1);
;     const char* la = lds + st * 32768; const char* lb = la + 16384;
;     bf16x8 af[2][4], bfv[2][4];
; #pragma unroll
;     for (int kc = 0; kc < 2; kc++) {
; #pragma unroll
;       for (int m = 0; m < 4; m++) { const int row = wr * 64 + m * 16 + fr; af[kc][m] = *(const bf16x8*)(la + (row * 8 + ((kc * 4 + fq) ^ ((row >> 1) & 7))) * 16); }
; #pragma unroll
;       for (int n = 0; n < 4; n++) { const int row = wc * 64 + n * 16 + fr; bfv[kc][n] = *(const bf16x8*)(lb + (row * 8 + ((kc * 4 + fq) ^ ((row >> 1) & 7))) * 16); }
;     }
;     __builtin_amdgcn_s_setprio(1);
; #pragma unroll
;     for (int kc = 0; kc < 2; kc++)
; #pragma unroll
;       for (int m = 0; m < 4; m++)
; #pragma unroll
;         for (int n = 0; n < 4; n++) acc[m][n] = __builtin_amdgcn_mfma_f32_16x16x32_bf16(bfv[kc][n], af[kc][m], acc[m][n], 0, 0, 0);
;     __builtin_amdgcn_s_setprio(0);
;     asm volatile("s_waitcnt vmcnt(0) lgkmcnt(0)" ::: "memory"); __builtin_amdgcn_s_barrier(); asm volatile("" ::: "memory");
;   }
	v_add_u32_e32 v0, 0, v85
	ds_read_b128 v[68:71], v0 offset:32768
	ds_read_b128 v[72:75], v0 offset:34816
	ds_read_b128 v[76:79], v0 offset:36864
	ds_read_b128 v[86:89], v0 offset:38912
	v_add_u32_e32 v0, 0, v84
	ds_read_b128 v[90:93], v0 offset:49152
	ds_read_b128 v[94:97], v0 offset:51200
	ds_read_b128 v[98:101], v0 offset:53248
	ds_read_b128 v[102:105], v0 offset:55296
	v_add_u32_e32 v0, 0, v83
	s_add_u32 s30, s46, s35
	ds_read_b128 v[80:83], v0 offset:32768
	ds_read_b128 v[106:109], v0 offset:34816
	ds_read_b128 v[110:113], v0 offset:36864
	ds_read_b128 v[114:117], v0 offset:38912
	v_add_u32_e32 v0, 0, v2
	s_addc_u32 s31, s47, 0
	ds_read_b128 v[118:121], v0 offset:49152
	ds_read_b128 v[122:125], v0 offset:51200
	ds_read_b128 v[126:129], v0 offset:53248
	ds_read_b128 v[130:133], v0 offset:55296
	s_add_u32 s36, s46, s36
	s_addc_u32 s37, s47, 0
	s_add_u32 s34, s30, 0x65a8000
	s_addc_u32 s35, s31, 0
	s_add_u32 s30, s36, 0xff9c000
	s_addc_u32 s31, s37, 0
	s_setprio 1
	s_waitcnt lgkmcnt(0)
	v_mfma_f32_16x16x32_bf16 v[56:59], v[98:101], v[68:71], v[56:59]
	v_mfma_f32_16x16x32_bf16 v[48:51], v[90:93], v[72:75], v[48:51]
	v_mfma_f32_16x16x32_bf16 v[44:47], v[94:97], v[72:75], v[44:47]
	v_mfma_f32_16x16x32_bf16 v[40:43], v[98:101], v[72:75], v[40:43]
	v_mfma_f32_16x16x32_bf16 v[36:39], v[102:105], v[72:75], v[36:39]
	v_mfma_f32_16x16x32_bf16 v[32:35], v[90:93], v[76:79], v[32:35]
	v_mfma_f32_16x16x32_bf16 v[28:31], v[94:97], v[76:79], v[28:31]
	v_mfma_f32_16x16x32_bf16 v[24:27], v[98:101], v[76:79], v[24:27]
	v_mfma_f32_16x16x32_bf16 v[20:23], v[102:105], v[76:79], v[20:23]
	v_mfma_f32_16x16x32_bf16 v[16:19], v[90:93], v[86:89], v[16:19]
	v_mfma_f32_16x16x32_bf16 v[12:15], v[94:97], v[86:89], v[12:15]
	v_mfma_f32_16x16x32_bf16 v[8:11], v[98:101], v[86:89], v[8:11]
	v_mfma_f32_16x16x32_bf16 v[4:7], v[102:105], v[86:89], v[4:7]
	v_mfma_f32_16x16x32_bf16 v[64:67], v[90:93], v[68:71], v[64:67]
	v_mfma_f32_16x16x32_bf16 v[60:63], v[94:97], v[68:71], v[60:63]
	v_mfma_f32_16x16x32_bf16 v[52:55], v[102:105], v[68:71], v[52:55]
	v_mfma_f32_16x16x32_bf16 v[56:59], v[126:129], v[80:83], v[56:59]
	v_mfma_f32_16x16x32_bf16 v[48:51], v[118:121], v[106:109], v[48:51]
	v_mfma_f32_16x16x32_bf16 v[44:47], v[122:125], v[106:109], v[44:47]
	v_mfma_f32_16x16x32_bf16 v[40:43], v[126:129], v[106:109], v[40:43]
	v_mfma_f32_16x16x32_bf16 v[36:39], v[130:133], v[106:109], v[36:39]
	v_mfma_f32_16x16x32_bf16 v[32:35], v[118:121], v[110:113], v[32:35]
	v_mfma_f32_16x16x32_bf16 v[28:31], v[122:125], v[110:113], v[28:31]
	v_mfma_f32_16x16x32_bf16 v[24:27], v[126:129], v[110:113], v[24:27]
	v_mfma_f32_16x16x32_bf16 v[20:23], v[130:133], v[110:113], v[20:23]
	v_mfma_f32_16x16x32_bf16 v[16:19], v[118:121], v[114:117], v[16:19]
	v_mfma_f32_16x16x32_bf16 v[12:15], v[122:125], v[114:117], v[12:15]
	v_mfma_f32_16x16x32_bf16 v[8:11], v[126:129], v[114:117], v[8:11]
	v_mfma_f32_16x16x32_bf16 v[4:7], v[130:133], v[114:117], v[4:7]
	v_mfma_f32_16x16x32_bf16 v[64:67], v[118:121], v[80:83], v[64:67]
	v_mfma_f32_16x16x32_bf16 v[60:63], v[122:125], v[80:83], v[60:63]
	v_mfma_f32_16x16x32_bf16 v[68:71], v[130:133], v[80:83], v[52:55]
	s_setprio 0
	v_mov_b32_e32 v0, v198
	s_waitcnt vmcnt(0) lgkmcnt(0)
	s_barrier
; __device__ __forceinline__ unsigned pk2(float lo, float hi) { unsigned r; asm("v_cvt_pk_bf16_f32 %0, %1, %2" : "=v"(r) : "v"(lo), "v"(hi)); return r; }
; __device__ __forceinline__ float bflo(unsigned u) { return __uint_as_float(u << 16); }
; __device__ __forceinline__ float bfhi(unsigned u) { return __uint_as_float(u & 0xffff0000u); }
; __device__ __forceinline__ void gemm_RES(const bf16_t* A, int K, const bf16_t* Bt, const float* xin, float* xout, bf16_t* xb, float* rss, int item, char* lds) {
;     ...
; #pragma unroll
;   for (int m = 0; m < 4; m++) {
;     const int rowg = m0 + wr * 64 + m * 16 + fr;
;     const size_t ro = (size_t)rowg * DM;
;     float sq = 0.f;
; #pragma unroll
;     for (int n = 0; n < 4; n++) {
;       const int col = n0 + wc * 64 + n * 16 + fq * 4;
;       f32x4 xv = *(const f32x4*)(xin + ro + col);
;       const f32x4 xn = xv + acc[m][n];
;       *(f32x4*)(xout + ro + col) = xn;
;       u32x2 w; w[0] = pk2(xn[0], xn[1]); w[1] = pk2(xn[2], xn[3]); *(u32x2*)(xb + ro + col) = w;
;       const float b0 = bflo(w[0]), b1 = bfhi(w[0]), b2 = bflo(w[1]), b3 = bfhi(w[1]);
;       sq += b0 * b0 + b1 * b1 + b2 * b2 + b3 * b3;
;     }
;     sq += __shfl_xor(sq, 16); sq += __shfl_xor(sq, 32);
;     if (fq == 0) unsafeAtomicAdd(rss + rowg, sq);
;   }
	v_readlane_b32 s4, v252, 35
	v_ashrrev_i32_e32 v2, 1, v0
	v_and_b32_e32 v2, 0xffffffc0, v2
	v_add_u32_e32 v2, s3, v2
	v_bfe_u32 v82, v0, 4, 2
	v_and_or_b32 v52, v0, 15, v2
	v_and_b32_e32 v1, 64, v0
	v_lshlrev_b32_e32 v0, 2, v82
	v_ashrrev_i32_e32 v53, 31, v52
	v_or3_b32 v78, v0, v1, s2
	v_lshlrev_b64 v[54:55], 12, v[52:53]
	v_lshl_add_u64 v[0:1], s[26:27], 0, v[54:55]
	v_lshlrev_b32_e32 v2, 2, v78
	v_lshl_add_u64 v[76:77], v[0:1], 0, v[2:3]
	global_load_dwordx4 v[72:75], v[76:77], off
	v_lshlrev_b32_e32 v0, 1, v78
	v_lshlrev_b64 v[78:79], 11, v[52:53]
	v_readlane_b32 s18, v252, 49
	v_readlane_b32 s19, v252, 50
	v_mov_b32_e32 v1, v3
	v_lshl_add_u64 v[78:79], s[34:35], 0, v[78:79]
	v_lshl_add_u64 v[54:55], s[18:19], 0, v[54:55]
	v_lshl_add_u64 v[80:81], v[54:55], 0, v[2:3]
	v_lshl_add_u64 v[78:79], v[78:79], 0, v[0:1]
	v_readlane_b32 s5, v252, 36
	v_readlane_b32 s6, v252, 37
	v_readlane_b32 s7, v252, 38
	v_readlane_b32 s8, v252, 39
	v_readlane_b32 s9, v252, 40
	v_readlane_b32 s10, v252, 41
	v_readlane_b32 s11, v252, 42
	v_readlane_b32 s12, v252, 43
	v_readlane_b32 s13, v252, 44
	v_readlane_b32 s14, v252, 45
	v_readlane_b32 s15, v252, 46
	v_readlane_b32 s16, v252, 47
	v_readlane_b32 s17, v252, 48
	s_waitcnt vmcnt(0)
	v_pk_add_f32 v[66:67], v[66:67], v[74:75]
	v_pk_add_f32 v[64:65], v[64:65], v[72:73]
	global_store_dwordx4 v[80:81], v[64:67], off
	v_cvt_pk_bf16_f32 v54, v64, v65
	v_cvt_pk_bf16_f32 v55, v66, v67
	global_store_dwordx2 v[78:79], v[54:55], off
	global_load_dwordx4 v[64:67], v[76:77], off offset:64
	s_waitcnt vmcnt(0)
	v_pk_add_f32 v[62:63], v[62:63], v[66:67]
	v_pk_add_f32 v[60:61], v[60:61], v[64:65]
	global_store_dwordx4 v[80:81], v[60:63], off offset:64
	v_cvt_pk_bf16_f32 v64, v60, v61
	v_cvt_pk_bf16_f32 v65, v62, v63
	global_store_dwordx2 v[78:79], v[64:65], off offset:32
	global_load_dwordx4 v[60:63], v[76:77], off offset:128
	v_lshlrev_b32_e32 v66, 16, v54
	v_and_b32_e32 v54, 0xffff0000, v54
	v_mul_f32_e32 v54, v54, v54
	v_lshlrev_b32_e32 v67, 16, v55
	v_fmac_f32_e32 v54, v66, v66
	v_and_b32_e32 v55, 0xffff0000, v55
	v_fmac_f32_e32 v54, v67, v67
	v_fmac_f32_e32 v54, v55, v55
	v_lshlrev_b32_e32 v55, 16, v64
	v_and_b32_e32 v64, 0xffff0000, v64
	v_mul_f32_e32 v64, v64, v64
	v_lshlrev_b32_e32 v66, 16, v65
	v_fmac_f32_e32 v64, v55, v55
	v_and_b32_e32 v65, 0xffff0000, v65
	v_fmac_f32_e32 v64, v66, v66
	v_fmac_f32_e32 v64, v65, v65
	v_add_f32_e32 v54, v54, v64
	s_waitcnt vmcnt(0)
	v_pk_add_f32 v[58:59], v[58:59], v[62:63]
	v_pk_add_f32 v[56:57], v[56:57], v[60:61]
	global_store_dwordx4 v[80:81], v[56:59], off offset:128
	v_cvt_pk_bf16_f32 v62, v56, v57
	v_cvt_pk_bf16_f32 v63, v58, v59
	global_store_dwordx2 v[78:79], v[62:63], off offset:64
	global_load_dwordx4 v[58:61], v[76:77], off offset:192
	v_lshlrev_b32_e32 v55, 16, v62
	v_and_b32_e32 v62, 0xffff0000, v62
	v_mul_f32_e32 v62, v62, v62
	v_lshlrev_b32_e32 v64, 16, v63
	v_fmac_f32_e32 v62, v55, v55
	v_and_b32_e32 v63, 0xffff0000, v63
	v_fmac_f32_e32 v62, v64, v64
	v_fmac_f32_e32 v62, v63, v63
	v_add_f32_e32 v54, v54, v62
	v_and_b32_e32 v57, 64, v218
	v_xor_b32_e32 v56, 16, v218
	v_add_u32_e32 v57, 64, v57
	v_cmp_lt_i32_e32 vcc, v56, v57
	s_waitcnt vmcnt(0)
	v_pk_add_f32 v[58:59], v[68:69], v[58:59]
	s_nop 0
	v_cvt_pk_bf16_f32 v62, v58, v59
	v_pk_add_f32 v[60:61], v[70:71], v[60:61]
	v_and_b32_e32 v64, 0xffff0000, v62
	v_lshlrev_b32_e32 v55, 16, v62
	v_mul_f32_e32 v64, v64, v64
	v_cvt_pk_bf16_f32 v63, v60, v61
	v_fmac_f32_e32 v64, v55, v55
	v_lshlrev_b32_e32 v65, 16, v63
	v_and_b32_e32 v66, 0xffff0000, v63
	v_fmac_f32_e32 v64, v65, v65
	v_cndmask_b32_e32 v56, v218, v56, vcc
	v_fmac_f32_e32 v64, v66, v66
	v_lshlrev_b32_e32 v56, 2, v56
	v_add_f32_e32 v54, v54, v64
	ds_bpermute_b32 v55, v56, v54
	v_xor_b32_e32 v64, 32, v218
	v_cmp_lt_i32_e32 vcc, v64, v57
	global_store_dwordx4 v[80:81], v[58:61], off offset:192
	global_store_dwordx2 v[78:79], v[62:63], off offset:96
	v_cndmask_b32_e32 v57, v218, v64, vcc
	s_waitcnt lgkmcnt(0)
	v_add_f32_e32 v54, v54, v55
	v_lshlrev_b32_e32 v57, 2, v57
	ds_bpermute_b32 v55, v57, v54
	v_cmp_eq_u32_e32 vcc, 0, v82
	s_and_saveexec_b64 s[36:37], vcc
	s_cbranch_execz .LBB0_129
	v_lshl_add_u64 v[58:59], v[52:53], 2, s[30:31]
	s_waitcnt lgkmcnt(0)
	v_add_f32_e32 v53, v54, v55
	global_atomic_add_f32 v[58:59], v53, off

; __device__ __forceinline__ unsigned char* WS(const Params& p) { unsigned z = 0; asm volatile("" : "+s"(z)); return p.ws + z; }
; __device__ __forceinline__ int opaque_tid() { int t = threadIdx.x; asm volatile("" : "+v"(t)); return t; }
; __device__ __forceinline__ void gemm_mainloop_d(const bf16_t* __restrict__ Ap, int lda, const bf16_t* __restrict__ Bt, int K,
;                                                 int m0, int n0, f32x4 (&acc)[4][4], char* lds) {
;   const int tid = opaque_tid(), lane = tid & 63, wid = tid >> 6, wr = wid >> 1, wc = wid & 1, fr = lane & 15, fq = lane >> 4;
; #pragma unroll
;   for (int m = 0; m < 4; m++)
; #pragma unroll
;     for (int n = 0; n < 4; n++) acc[m][n] = (f32x4){0.f, 0.f, 0.f, 0.f};
;   const int nk = K >> 6;
;   const int lrow = tid >> 3, cph = tid & 7;
;   auto dma = [&](int kt, int st) {
;     char* la = lds + st * 32768; char* lb = la + 16384;
; #pragma unroll
;     for (int i = 0; i < 4; i++) {
;       const int row = i * 32 + lrow; const int c = cph ^ ((row >> 1) & 7);
;       __builtin_amdgcn_global_load_lds((const unsigned*)(Ap + (size_t)(m0 + row) * lda + kt * 64 + c * 8), (__attribute__((address_space(3))) unsigned*)(la + i * 4096 + tid * 16), 16, 0, 0);
;       __builtin_amdgcn_global_load_lds((const unsigned*)(Bt + (size_t)(n0 + row) * K + kt * 64 + c * 8), (__attribute__((address_space(3))) unsigned*)(lb + i * 4096 + tid * 16), 16, 0, 0);
;     }
;   };
;   dma(0, 0);
;   asm volatile("s_waitcnt vmcnt(0)" ::: "memory"); __builtin_amdgcn_s_barrier(); asm volatile("" ::: "memory");
; __device__ __forceinline__ void gemm_A(const Params& p, int item, char* lds) {
;   const int mt = item / 18, nt = item % 18; const int m0 = mt * 128, n0 = nt * 128;
;   f32x4 acc[4][4];
;   gemm_mainloop_d((const bf16_t*)(WS(p) + OFF_XB), DM, (const bf16_t*)(WS(p) + OFF_WIN), DM, m0, n0, acc, lds);
.LBB0_656:
	s_lshr_b32 s3, s66, 3
	s_mul_hi_u32 s30, s3, 0xe38e38f
	s_mul_i32 s31, s30, 18
	s_sub_u32 s2, s3, s31
	s_and_b32 s31, s66, 7
	s_lshl_b32 s30, s30, 3
	s_add_u32 s30, s30, s31
	s_lshl_b32 s24, s30, 7
	s_lshl_b32 s3, s2, 7
	s_mov_b32 s30, 0
	s_mov_b32 s31, 0
	v_mov_b32_e32 v20, v198
	s_add_u32 s26, s46, s30
	s_addc_u32 s27, s47, 0
	v_ashrrev_i32_e32 v16, 3, v20
	v_lshrrev_b32_e32 v23, 1, v16
	v_add_u32_e32 v0, s24, v16
	s_add_u32 s28, s26, 0x65a8000
	v_xor_b32_e32 v2, v23, v20
	v_ashrrev_i32_e32 v1, 31, v0
	s_addc_u32 s29, s27, 0
	v_lshlrev_b64 v[0:1], 11, v[0:1]
	v_lshlrev_b32_e32 v2, 4, v2
	v_lshl_add_u32 v82, v20, 4, 0
	s_waitcnt lgkmcnt(0)
	v_lshl_add_u64 v[4:5], s[28:29], 0, v[0:1]
	v_and_b32_e32 v2, 0x70, v2
	v_readfirstlane_b32 s34, v82
	s_add_u32 s26, s46, s31
	v_lshl_add_u64 v[4:5], v[4:5], 0, v[2:3]
	s_mov_b32 m0, s34
	s_addc_u32 s27, s47, 0
	global_load_lds_dwordx4 v[4:5], off
	v_add_u32_e32 v4, s3, v16
	s_add_u32 s26, s26, 0x8000
	v_ashrrev_i32_e32 v5, 31, v4
	s_addc_u32 s27, s27, 0
	v_lshlrev_b64 v[4:5], 11, v[4:5]
	v_add_u32_e32 v8, 0x4000, v82
	v_lshl_add_u64 v[6:7], s[26:27], 0, v[4:5]
	v_readfirstlane_b32 s34, v8
	v_lshl_add_u64 v[6:7], v[6:7], 0, v[2:3]
	s_mov_b32 m0, s34
	v_add_u32_e32 v10, 32, v16
	global_load_lds_dwordx4 v[6:7], off
	v_add_u32_e32 v6, s24, v10
	v_ashrrev_i32_e32 v7, 31, v6
	v_lshlrev_b64 v[6:7], 11, v[6:7]
	v_add_u32_e32 v11, 0x1000, v82
	v_lshl_add_u64 v[8:9], s[28:29], 0, v[6:7]
	v_readfirstlane_b32 s34, v11
	v_lshl_add_u64 v[8:9], v[8:9], 0, v[2:3]
	s_mov_b32 m0, s34
	v_add_u32_e32 v12, 0x5000, v82
	global_load_lds_dwordx4 v[8:9], off
	v_add_u32_e32 v8, s3, v10
	v_ashrrev_i32_e32 v9, 31, v8
	v_lshlrev_b64 v[8:9], 11, v[8:9]
	v_lshl_add_u64 v[10:11], s[26:27], 0, v[8:9]
	v_readfirstlane_b32 s34, v12
	v_lshl_add_u64 v[10:11], v[10:11], 0, v[2:3]
	s_mov_b32 m0, s34
	v_add_u32_e32 v14, 64, v16
	global_load_lds_dwordx4 v[10:11], off
	v_add_u32_e32 v10, s24, v14
	v_ashrrev_i32_e32 v11, 31, v10
	v_lshlrev_b64 v[10:11], 11, v[10:11]
	v_add_u32_e32 v15, 0x2000, v82
	v_lshl_add_u64 v[12:13], s[28:29], 0, v[10:11]
	v_readfirstlane_b32 s34, v15
	v_lshl_add_u64 v[12:13], v[12:13], 0, v[2:3]
	s_mov_b32 m0, s34
	v_add_u32_e32 v17, 0x6000, v82
	global_load_lds_dwordx4 v[12:13], off
	v_add_u32_e32 v12, s3, v14
	v_ashrrev_i32_e32 v13, 31, v12
	v_lshlrev_b64 v[12:13], 11, v[12:13]
	v_lshl_add_u64 v[14:15], s[26:27], 0, v[12:13]
	v_readfirstlane_b32 s34, v17
	v_lshl_add_u64 v[14:15], v[14:15], 0, v[2:3]
	s_mov_b32 m0, s34
	v_add_u32_e32 v18, 0x60, v16
	global_load_lds_dwordx4 v[14:15], off
	v_add_u32_e32 v14, s24, v18
	v_ashrrev_i32_e32 v15, 31, v14
	v_lshlrev_b64 v[14:15], 11, v[14:15]
	v_add_u32_e32 v19, 0x3000, v82
	v_lshl_add_u64 v[16:17], s[28:29], 0, v[14:15]
	v_readfirstlane_b32 s28, v19
	v_lshl_add_u64 v[16:17], v[16:17], 0, v[2:3]
	s_mov_b32 m0, s28
	s_mov_b32 s4, 0x1ffffc0
	global_load_lds_dwordx4 v[16:17], off
	v_add_u32_e32 v16, s3, v18
	v_ashrrev_i32_e32 v17, 31, v16
	v_lshlrev_b64 v[16:17], 11, v[16:17]
	v_lshl_add_u64 v[18:19], s[26:27], 0, v[16:17]
	v_lshl_add_u64 v[18:19], v[18:19], 0, v[2:3]
	v_add_u32_e32 v2, 0x7000, v82
	v_lshrrev_b32_e32 v21, 4, v20
	v_readfirstlane_b32 s26, v2
	s_mov_b32 m0, s26
	v_and_b32_e32 v2, 15, v20
	global_load_lds_dwordx4 v[18:19], off
	v_lshrrev_b32_e32 v18, 1, v20
	v_bfe_u32 v22, v20, 4, 2
	v_and_or_b32 v2, v18, s4, v2
	v_bfe_u32 v18, v20, 1, 3
	v_lshlrev_b32_e32 v19, 7, v20
	v_bitop3_b32 v21, v21, v18, 3 bitop3:0x6c
	v_bitop3_b32 v18, v22, v18, 4 bitop3:0x36
	v_readlane_b32 s4, v254, 44
	v_and_b32_e32 v19, 0x2780, v19
	v_lshlrev_b32_e32 v21, 4, v21
	v_lshlrev_b32_e32 v2, 7, v2
	v_lshlrev_b32_e32 v18, 4, v18
	s_add_u32 s26, s4, s30
	v_readlane_b32 s4, v254, 45
	v_or_b32_e32 v85, v2, v21
	v_or_b32_e32 v83, v18, v2
	v_or_b32_e32 v2, v18, v19
	v_bitop3_b32 v18, v23, 7, v20 bitop3:0x48
	s_addc_u32 s27, s4, 0
	v_readlane_b32 s4, v254, 62
	v_lshlrev_b32_e32 v18, 4, v18
	s_add_u32 s28, s4, s31
	v_readlane_b32 s4, v254, 63
	s_waitcnt vmcnt(0)
	s_barrier
	v_or_b32_e32 v4, v4, v18
	s_addc_u32 s29, s4, 0
	v_or_b32_e32 v0, v0, v18
	s_waitcnt vmcnt(0)
	v_lshl_add_u64 v[68:69], s[28:29], 0, v[4:5]
	v_or_b32_e32 v6, v6, v18
	v_or_b32_e32 v8, v8, v18
	v_or_b32_e32 v10, v10, v18
	v_or_b32_e32 v12, v12, v18
	v_or_b32_e32 v14, v14, v18
	v_or_b32_e32 v16, v16, v18
	v_mov_b32_e32 v4, 0
	s_mov_b32 s25, 0
	v_or_b32_e32 v84, v21, v19
	v_lshl_add_u64 v[0:1], s[26:27], 0, v[0:1]
	v_lshl_add_u64 v[70:71], s[26:27], 0, v[6:7]
	v_lshl_add_u64 v[72:73], s[28:29], 0, v[8:9]
	v_lshl_add_u64 v[74:75], s[26:27], 0, v[10:11]
	v_lshl_add_u64 v[76:77], s[28:29], 0, v[12:13]
	v_lshl_add_u64 v[78:79], s[26:27], 0, v[14:15]
	v_lshl_add_u64 v[80:81], s[28:29], 0, v[16:17]
	s_mov_b64 s[26:27], 0
	v_mov_b32_e32 v5, v4
	v_mov_b32_e32 v6, v4
	v_mov_b32_e32 v7, v4
	v_mov_b32_e32 v8, v4
	v_mov_b32_e32 v9, v4
	v_mov_b32_e32 v10, v4
	v_mov_b32_e32 v11, v4
	v_mov_b32_e32 v12, v4
	v_mov_b32_e32 v13, v4
	v_mov_b32_e32 v14, v4
	v_mov_b32_e32 v15, v4
	v_mov_b32_e32 v16, v4
	v_mov_b32_e32 v17, v4
	v_mov_b32_e32 v18, v4
	v_mov_b32_e32 v19, v4
	v_mov_b32_e32 v20, v4
	v_mov_b32_e32 v21, v4
	v_mov_b32_e32 v22, v4
	v_mov_b32_e32 v23, v4
	v_mov_b32_e32 v24, v4
	v_mov_b32_e32 v25, v4
	v_mov_b32_e32 v26, v4
	v_mov_b32_e32 v27, v4
	v_mov_b32_e32 v28, v4
	v_mov_b32_e32 v29, v4
	v_mov_b32_e32 v30, v4
	v_mov_b32_e32 v31, v4
	v_mov_b32_e32 v32, v4
	v_mov_b32_e32 v33, v4
	v_mov_b32_e32 v34, v4
	v_mov_b32_e32 v35, v4
	v_mov_b32_e32 v36, v4
	v_mov_b32_e32 v37, v4
	v_mov_b32_e32 v38, v4
	v_mov_b32_e32 v39, v4
	v_mov_b32_e32 v40, v4
	v_mov_b32_e32 v41, v4
	v_mov_b32_e32 v42, v4
	v_mov_b32_e32 v43, v4
	v_mov_b32_e32 v44, v4
	v_mov_b32_e32 v45, v4
	v_mov_b32_e32 v46, v4
	v_mov_b32_e32 v47, v4
	v_mov_b32_e32 v48, v4
	v_mov_b32_e32 v49, v4
	v_mov_b32_e32 v50, v4
	v_mov_b32_e32 v51, v4
	v_mov_b32_e32 v52, v4
	v_mov_b32_e32 v53, v4
	v_mov_b32_e32 v54, v4
	v_mov_b32_e32 v55, v4
	v_mov_b32_e32 v56, v4
	v_mov_b32_e32 v57, v4
	v_mov_b32_e32 v58, v4
	v_mov_b32_e32 v59, v4
	v_mov_b32_e32 v60, v4
	v_mov_b32_e32 v61, v4
	v_mov_b32_e32 v62, v4
	v_mov_b32_e32 v63, v4
	v_mov_b32_e32 v64, v4
	v_mov_b32_e32 v65, v4
	v_mov_b32_e32 v66, v4
	v_mov_b32_e32 v67, v4
	v_subrev_u32_e32 v150, s46, v0
	v_subrev_u32_e32 v151, s46, v68
	v_subrev_u32_e32 v152, s46, v70
	v_subrev_u32_e32 v153, s46, v72
	v_subrev_u32_e32 v154, s46, v74
	v_subrev_u32_e32 v155, s46, v76
	v_subrev_u32_e32 v156, s46, v78
	v_subrev_u32_e32 v157, s46, v80
	v_readfirstlane_b32 vcc_hi, v82
; __device__ __forceinline__ void gemm_mainloop_d(const bf16_t* __restrict__ Ap, int lda, const bf16_t* __restrict__ Bt, int K,
;                                                 int m0, int n0, f32x4 (&acc)[4][4], char* lds) {
;     ...
;   for (int kt = 0; kt < nk; kt++) {
;     const int st = kt & 1;
;     if (kt + 1 < nk) dma(kt + 1, st ^ 1);
;     const char* la = lds + st * 32768; const char* lb = la + 16384;
;     bf16x8 af[2][4], bfv[2][4];
; #pragma unroll
;     for (int kc = 0; kc < 2; kc++) {
; #pragma unroll
;       for (int m = 0; m < 4; m++) { const int row = wr * 64 + m * 16 + fr; af[kc][m] = *(const bf16x8*)(la + (row * 8 + ((kc * 4 + fq) ^ ((row >> 1) & 7))) * 16); }
; #pragma unroll
;       for (int n = 0; n < 4; n++) { const int row = wc * 64 + n * 16 + fr; bfv[kc][n] = *(const bf16x8*)(lb + (row * 8 + ((kc * 4 + fq) ^ ((row >> 1) & 7))) * 16); }
;     }
;     __builtin_amdgcn_s_setprio(1);
; #pragma unroll
;     for (int kc = 0; kc < 2; kc++)
; #pragma unroll
;       for (int m = 0; m < 4; m++)
; #pragma unroll
;         for (int n = 0; n < 4; n++) acc[m][n] = __builtin_amdgcn_mfma_f32_16x16x32_bf16(bfv[kc][n], af[kc][m], acc[m][n], 0, 0, 0);
;     __builtin_amdgcn_s_setprio(0);
;     asm volatile("s_waitcnt vmcnt(0) lgkmcnt(0)" ::: "memory"); __builtin_amdgcn_s_barrier(); asm volatile("" ::: "memory");
;   }
.LBB0_657:
	s_and_b32 s28, s25, 0x8000
	s_xor_b32 s29, s28, 0x8000
	s_add_i32 s29, s29, vcc_hi
	s_mov_b32 m0, s29
	s_add_i32 vcc_lo, s29, 0x4000
	global_load_lds_dwordx4 v150, s[46:47]
	s_mov_b32 m0, vcc_lo
	s_add_i32 vcc_lo, s29, 0x1000
	global_load_lds_dwordx4 v151, s[46:47]
	s_mov_b32 m0, vcc_lo
	s_add_i32 vcc_lo, s29, 0x5000
	global_load_lds_dwordx4 v152, s[46:47]
	s_mov_b32 m0, vcc_lo
	s_add_i32 vcc_lo, s29, 0x2000
	global_load_lds_dwordx4 v153, s[46:47]
	s_mov_b32 m0, vcc_lo
	s_add_i32 vcc_lo, s29, 0x6000
	global_load_lds_dwordx4 v154, s[46:47]
	s_mov_b32 m0, vcc_lo
	s_add_i32 vcc_lo, s29, 0x3000
	global_load_lds_dwordx4 v155, s[46:47]
	s_mov_b32 m0, vcc_lo
	s_add_i32 vcc_lo, s29, 0x7000
	global_load_lds_dwordx4 v156, s[46:47]
	s_mov_b32 m0, vcc_lo
	s_nop 0
	global_load_lds_dwordx4 v157, s[46:47]
	v_add_u32_e32 v150, 0x80, v150
	v_add_u32_e32 v151, 0x80, v151
	v_add_u32_e32 v152, 0x80, v152
	v_add_u32_e32 v153, 0x80, v153
	v_add_u32_e32 v154, 0x80, v154
	v_add_u32_e32 v155, 0x80, v155
	v_add_u32_e32 v156, 0x80, v156
	v_add_u32_e32 v157, 0x80, v157
	v_add_u32_e32 v98, s28, v85
	v_add_u32_e32 v114, s28, v84
	v_add_u32_e32 v130, s28, v83
	v_add_u32_e32 v146, s28, v2
	ds_read_b128 v[86:89], v98
	ds_read_b128 v[90:93], v98 offset:2048
	ds_read_b128 v[94:97], v98 offset:4096
	ds_read_b128 v[98:101], v98 offset:6144
	ds_read_b128 v[102:105], v114 offset:16384
	ds_read_b128 v[106:109], v114 offset:18432
	ds_read_b128 v[110:113], v114 offset:20480
	ds_read_b128 v[114:117], v114 offset:22528
	ds_read_b128 v[118:121], v130
	ds_read_b128 v[122:125], v130 offset:2048
	ds_read_b128 v[126:129], v130 offset:4096
	ds_read_b128 v[130:133], v130 offset:6144
	ds_read_b128 v[134:137], v146 offset:16384
	ds_read_b128 v[138:141], v146 offset:18432
	ds_read_b128 v[142:145], v146 offset:20480
	ds_read_b128 v[146:149], v146 offset:22528
	s_setprio 1
	s_waitcnt lgkmcnt(0)
	v_mfma_f32_16x16x32_bf16 v[64:67], v[102:105], v[86:89], v[64:67]
	v_mfma_f32_16x16x32_bf16 v[60:63], v[106:109], v[86:89], v[60:63]
	v_mfma_f32_16x16x32_bf16 v[56:59], v[110:113], v[86:89], v[56:59]
	v_mfma_f32_16x16x32_bf16 v[52:55], v[114:117], v[86:89], v[52:55]
	v_mfma_f32_16x16x32_bf16 v[48:51], v[102:105], v[90:93], v[48:51]
	v_mfma_f32_16x16x32_bf16 v[44:47], v[106:109], v[90:93], v[44:47]
	v_mfma_f32_16x16x32_bf16 v[40:43], v[110:113], v[90:93], v[40:43]
	v_mfma_f32_16x16x32_bf16 v[36:39], v[114:117], v[90:93], v[36:39]
	v_mfma_f32_16x16x32_bf16 v[32:35], v[102:105], v[94:97], v[32:35]
	v_mfma_f32_16x16x32_bf16 v[28:31], v[106:109], v[94:97], v[28:31]
	v_mfma_f32_16x16x32_bf16 v[24:27], v[110:113], v[94:97], v[24:27]
	v_mfma_f32_16x16x32_bf16 v[20:23], v[114:117], v[94:97], v[20:23]
	v_mfma_f32_16x16x32_bf16 v[16:19], v[102:105], v[98:101], v[16:19]
	v_mfma_f32_16x16x32_bf16 v[12:15], v[106:109], v[98:101], v[12:15]
	v_mfma_f32_16x16x32_bf16 v[8:11], v[110:113], v[98:101], v[8:11]
	v_mfma_f32_16x16x32_bf16 v[4:7], v[114:117], v[98:101], v[4:7]
	v_mfma_f32_16x16x32_bf16 v[64:67], v[134:137], v[118:121], v[64:67]
	v_mfma_f32_16x16x32_bf16 v[60:63], v[138:141], v[118:121], v[60:63]
	v_mfma_f32_16x16x32_bf16 v[56:59], v[142:145], v[118:121], v[56:59]
	v_mfma_f32_16x16x32_bf16 v[52:55], v[146:149], v[118:121], v[52:55]
	v_mfma_f32_16x16x32_bf16 v[48:51], v[134:137], v[122:125], v[48:51]
	v_mfma_f32_16x16x32_bf16 v[44:47], v[138:141], v[122:125], v[44:47]
	v_mfma_f32_16x16x32_bf16 v[40:43], v[142:145], v[122:125], v[40:43]
	v_mfma_f32_16x16x32_bf16 v[36:39], v[146:149], v[122:125], v[36:39]
	v_mfma_f32_16x16x32_bf16 v[32:35], v[134:137], v[126:129], v[32:35]
	v_mfma_f32_16x16x32_bf16 v[28:31], v[138:141], v[126:129], v[28:31]
	v_mfma_f32_16x16x32_bf16 v[24:27], v[142:145], v[126:129], v[24:27]
	v_mfma_f32_16x16x32_bf16 v[20:23], v[146:149], v[126:129], v[20:23]
	v_mfma_f32_16x16x32_bf16 v[16:19], v[134:137], v[130:133], v[16:19]
	v_mfma_f32_16x16x32_bf16 v[12:15], v[138:141], v[130:133], v[12:15]
	v_mfma_f32_16x16x32_bf16 v[8:11], v[142:145], v[130:133], v[8:11]
	v_mfma_f32_16x16x32_bf16 v[4:7], v[146:149], v[130:133], v[4:7]
	s_setprio 0
	s_waitcnt vmcnt(0) lgkmcnt(0)
	s_barrier
	s_add_u32 s26, s26, 0x80
	s_addc_u32 s27, s27, 0
	s_add_i32 s25, s25, 0x8000
	s_cmpk_eq_i32 s26, 0x780
	s_cbranch_scc0 .LBB0_657
; __device__ __forceinline__ unsigned char* WS(const Params& p) { unsigned z = 0; asm volatile("" : "+s"(z)); return p.ws + z; }
; __device__ __forceinline__ unsigned pk2(float lo, float hi) { unsigned r; asm("v_cvt_pk_bf16_f32 %0, %1, %2" : "=v"(r) : "v"(lo), "v"(hi)); return r; }
; __device__ __forceinline__ void gemm_mainloop_d(const bf16_t* __restrict__ Ap, int lda, const bf16_t* __restrict__ Bt, int K,
;                                                 int m0, int n0, f32x4 (&acc)[4][4], char* lds) {
;     ...
;   for (int kt = 0; kt < nk; kt++) {
;     const int st = kt & 1;
;     if (kt + 1 < nk) dma(kt + 1, st ^ 1);
;     const char* la = lds + st * 32768; const char* lb = la + 16384;
;     bf16x8 af[2][4], bfv[2][4];
; #pragma unroll
;     for (int kc = 0; kc < 2; kc++) {
; #pragma unroll
;       for (int m = 0; m < 4; m++) { const int row = wr * 64 + m * 16 + fr; af[kc][m] = *(const bf16x8*)(la + (row * 8 + ((kc * 4 + fq) ^ ((row >> 1) & 7))) * 16); }
; #pragma unroll
;       for (int n = 0; n < 4; n++) { const int row = wc * 64 + n * 16 + fr; bfv[kc][n] = *(const bf16x8*)(lb + (row * 8 + ((kc * 4 + fq) ^ ((row >> 1) & 7))) * 16); }
;     }
;     __builtin_amdgcn_s_setprio(1);
; #pragma unroll
;     for (int kc = 0; kc < 2; kc++)
; #pragma unroll
;       for (int m = 0; m < 4; m++)
; #pragma unroll
;         for (int n = 0; n < 4; n++) acc[m][n] = __builtin_amdgcn_mfma_f32_16x16x32_bf16(bfv[kc][n], af[kc][m], acc[m][n], 0, 0, 0);
;     __builtin_amdgcn_s_setprio(0);
;     asm volatile("s_waitcnt vmcnt(0) lgkmcnt(0)" ::: "memory"); __builtin_amdgcn_s_barrier(); asm volatile("" ::: "memory");
;   }
; __device__ __forceinline__ void gemm_A(const Params& p, int item, char* lds) {
;     ...
;   const float* rssg = (const float*)(WS(p) + OFF_RSS) + m0;
;   bf16_t* P = (bf16_t*)(WS(p) + OFF_P);
; #pragma unroll
;   for (int m = 0; m < 4; m++) {
;     const int rl = wr * 64 + m * 16 + fr; const float r = rsqrtf(rssg[rl] * (1.f / 1024.f) + 1e-6f);
;     float sq = 0.f;
; #pragma unroll
;     for (int n = 0; n < 4; n++) {
;       const int col = n0 + wc * 64 + n * 16 + fq * 4;
;       if (col < PIN) { f32x4 v = acc[m][n] * r; u32x2 w; w[0] = pk2(v[0], v[1]); w[1] = pk2(v[2], v[3]); *(u32x2*)(P + (size_t)(m0 + rl) * PIN + col) = w;
;         const float b0 = bflo(w[0]), b1 = bfhi(w[0]), b2 = bflo(w[1]), b3 = bfhi(w[1]); sq += b0 * b0 + b1 * b1 + b2 * b2 + b3 * b3; }
	v_add_u32_e32 v0, 0, v85
	ds_read_b128 v[68:71], v0 offset:32768
	ds_read_b128 v[72:75], v0 offset:34816
	ds_read_b128 v[76:79], v0 offset:36864
	ds_read_b128 v[86:89], v0 offset:38912
	v_add_u32_e32 v0, 0, v84
	ds_read_b128 v[90:93], v0 offset:49152
	ds_read_b128 v[94:97], v0 offset:51200
	ds_read_b128 v[98:101], v0 offset:53248
	ds_read_b128 v[102:105], v0 offset:55296
	v_add_u32_e32 v0, 0, v83
	ds_read_b128 v[80:83], v0 offset:32768
	ds_read_b128 v[106:109], v0 offset:34816
	ds_read_b128 v[110:113], v0 offset:36864
	ds_read_b128 v[114:117], v0 offset:38912
	v_add_u32_e32 v0, 0, v2
	ds_read_b128 v[118:121], v0 offset:49152
	ds_read_b128 v[122:125], v0 offset:51200
	ds_read_b128 v[126:129], v0 offset:53248
	ds_read_b128 v[130:133], v0 offset:55296
	s_setprio 1
	s_waitcnt lgkmcnt(0)
	v_mfma_f32_16x16x32_bf16 v[64:67], v[90:93], v[68:71], v[64:67]
	v_mfma_f32_16x16x32_bf16 v[60:63], v[94:97], v[68:71], v[60:63]
	v_mfma_f32_16x16x32_bf16 v[56:59], v[98:101], v[68:71], v[56:59]
	v_mfma_f32_16x16x32_bf16 v[52:55], v[102:105], v[68:71], v[52:55]
	v_mfma_f32_16x16x32_bf16 v[48:51], v[90:93], v[72:75], v[48:51]
	v_mfma_f32_16x16x32_bf16 v[44:47], v[94:97], v[72:75], v[44:47]
	v_mfma_f32_16x16x32_bf16 v[40:43], v[98:101], v[72:75], v[40:43]
	v_mfma_f32_16x16x32_bf16 v[36:39], v[102:105], v[72:75], v[36:39]
	v_mfma_f32_16x16x32_bf16 v[32:35], v[90:93], v[76:79], v[32:35]
	v_mfma_f32_16x16x32_bf16 v[28:31], v[94:97], v[76:79], v[28:31]
	v_mfma_f32_16x16x32_bf16 v[24:27], v[98:101], v[76:79], v[24:27]
	v_mfma_f32_16x16x32_bf16 v[20:23], v[102:105], v[76:79], v[20:23]
	v_mfma_f32_16x16x32_bf16 v[16:19], v[90:93], v[86:89], v[16:19]
	v_mfma_f32_16x16x32_bf16 v[12:15], v[94:97], v[86:89], v[12:15]
	v_mfma_f32_16x16x32_bf16 v[8:11], v[98:101], v[86:89], v[8:11]
	v_mfma_f32_16x16x32_bf16 v[4:7], v[102:105], v[86:89], v[4:7]
	v_mfma_f32_16x16x32_bf16 v[64:67], v[118:121], v[80:83], v[64:67]
	v_mfma_f32_16x16x32_bf16 v[60:63], v[122:125], v[80:83], v[60:63]
	v_mfma_f32_16x16x32_bf16 v[56:59], v[126:129], v[80:83], v[56:59]
	v_mfma_f32_16x16x32_bf16 v[52:55], v[130:133], v[80:83], v[52:55]
	v_mfma_f32_16x16x32_bf16 v[48:51], v[118:121], v[106:109], v[48:51]
	v_mfma_f32_16x16x32_bf16 v[44:47], v[122:125], v[106:109], v[44:47]
	v_mfma_f32_16x16x32_bf16 v[40:43], v[126:129], v[106:109], v[40:43]
	v_mfma_f32_16x16x32_bf16 v[36:39], v[130:133], v[106:109], v[36:39]
	v_mfma_f32_16x16x32_bf16 v[32:35], v[118:121], v[110:113], v[32:35]
	v_mfma_f32_16x16x32_bf16 v[28:31], v[122:125], v[110:113], v[28:31]
	v_mfma_f32_16x16x32_bf16 v[24:27], v[126:129], v[110:113], v[24:27]
	v_mfma_f32_16x16x32_bf16 v[20:23], v[130:133], v[110:113], v[20:23]
	v_mfma_f32_16x16x32_bf16 v[16:19], v[118:121], v[114:117], v[16:19]
	v_mfma_f32_16x16x32_bf16 v[12:15], v[122:125], v[114:117], v[12:15]
	v_mfma_f32_16x16x32_bf16 v[8:11], v[126:129], v[114:117], v[8:11]
	v_mfma_f32_16x16x32_bf16 v[4:7], v[130:133], v[114:117], v[4:7]
	s_setprio 0
	v_mov_b32_e32 v2, v198
	s_mov_b32 s25, s89
	s_waitcnt vmcnt(0) lgkmcnt(0)
	s_barrier
	s_add_u32 s28, s46, s25
	s_addc_u32 s29, s47, 0
	s_ashr_i32 s25, s24, 31
	v_and_b32_e32 v0, 15, v2
	s_lshl_b64 s[26:27], s[24:25], 2
	v_ashrrev_i32_e32 v1, 1, v2
	s_movk_i32 s4, 0xffc0
	s_add_u32 s28, s28, s26
	v_and_or_b32 v0, v1, s4, v0
	s_addc_u32 s29, s29, s27
	v_ashrrev_i32_e32 v1, 31, v0
	v_lshl_add_u64 v[70:71], v[0:1], 2, s[28:29]
	s_mov_b32 s28, 0xff8c000
	v_add_co_u32_e32 v68, vcc, s28, v70
	s_mov_b32 s25, s89
	s_nop 0
	v_addc_co_u32_e32 v69, vcc, 0, v71, vcc
	global_load_dword v69, v[68:69], off
	v_and_b32_e32 v68, 64, v2
	v_bfe_u32 v2, v2, 4, 2
	v_lshlrev_b32_e32 v72, 2, v2
	v_or3_b32 v68, v72, v68, s3
	s_add_u32 s3, s46, s25
	s_addc_u32 s25, s47, 0
	s_add_u32 s30, s3, 0x768000
	s_addc_u32 s31, s25, 0
	v_add_u32_e32 v74, s24, v0
	v_mov_b32_e32 v76, 0
	v_cmp_gt_i32_e64 s[34:35], s78, v68
	s_waitcnt vmcnt(0)
	v_fmamk_f32 v69, v69, 0x3a800000, v200
	v_mul_f32_e32 v72, 0x4b800000, v69
	v_cmp_gt_f32_e32 vcc, s83, v69
	s_nop 1
	v_cndmask_b32_e32 v69, v69, v72, vcc
	v_rsq_f32_e32 v69, v69
	v_mov_b64_e32 v[72:73], s[30:31]
	v_mad_i64_i32 v[72:73], s[28:29], v74, s69, v[72:73]
	v_mul_f32_e32 v74, 0x45800000, v69
	v_cndmask_b32_e32 v74, v69, v74, vcc
	v_mov_b32_e32 v75, v74
	v_ashrrev_i32_e32 v69, 31, v68
	s_and_saveexec_b64 s[28:29], s[34:35]
	s_cbranch_execz .LBB0_660
	v_mov_b32_e32 v76, v74
	v_mov_b32_e32 v77, v74
	v_pk_mul_f32 v[66:67], v[66:67], v[76:77]
	v_pk_mul_f32 v[64:65], v[64:65], v[74:75]
	s_nop 0
	v_cvt_pk_bf16_f32 v64, v64, v65
	v_cvt_pk_bf16_f32 v65, v66, v67
	v_lshl_add_u64 v[66:67], v[68:69], 1, v[72:73]
	global_store_dwordx2 v[66:67], v[64:65], off
	v_lshlrev_b32_e32 v66, 16, v64
	v_and_b32_e32 v67, 0xffff0000, v64
	v_pk_mul_f32 v[66:67], v[66:67], v[66:67]
	v_and_b32_e32 v64, 0xffff0000, v65
	v_lshlrev_b32_e32 v65, 16, v65
	v_pk_mul_f32 v[64:65], v[64:65], v[64:65]
	v_add_f32_e32 v66, v66, v67
	v_add_f32_e32 v65, v66, v65
	v_add_f32_e32 v76, v64, v65
